# v14 plus thin GEMMs: exact vmcnt counts on the loads-issued paths of the phase-I residual thin GEMM and LDS fragment reads pipelined over a ring of free registers with counted lgkmcnt in the A, G, H,
# speedup vs baseline: 1.0008x; 1.0008x over previous
.LBB0_414:
	s_bitcmp1_b32 s1, 0
	s_cselect_b32 s2, 0x4200, 0
	v_add_u32_e32 v160, s2, v159
	ds_read_b128 v[162:165], v160
	ds_read_b128 v[200:203], v160 offset:8448
	ds_read_b128 v[204:207], v160 offset:64
	ds_read_b128 v[208:211], v160 offset:8512
	ds_read_b128 v[214:217], v160 offset:128
	ds_read_b128 v[218:221], v160 offset:8576
	ds_read_b128 v[234:237], v160 offset:192
	ds_read_b128 v[238:241], v160 offset:8640
	ds_read_b128 v[242:245], v160 offset:256
	ds_read_b128 v[246:249], v160 offset:8704
	s_waitcnt lgkmcnt(9)
	v_mfma_f32_16x16x32_bf16 v[122:125], v[162:165], v[50:53], v[122:125]
	ds_read_b128 v[162:165], v160 offset:320
	s_waitcnt lgkmcnt(9)
	v_mfma_f32_16x16x32_bf16 v[126:129], v[200:203], v[50:53], v[126:129]
	ds_read_b128 v[200:203], v160 offset:8768
	s_waitcnt lgkmcnt(9)
	v_mfma_f32_16x16x32_bf16 v[122:125], v[204:207], v[54:57], v[122:125]
	ds_read_b128 v[204:207], v160 offset:384
	s_waitcnt lgkmcnt(9)
	v_mfma_f32_16x16x32_bf16 v[126:129], v[208:211], v[54:57], v[126:129]
	ds_read_b128 v[208:211], v160 offset:8832
	s_waitcnt lgkmcnt(9)
	v_mfma_f32_16x16x32_bf16 v[122:125], v[214:217], v[66:69], v[122:125]
	ds_read_b128 v[214:217], v160 offset:448
	s_waitcnt lgkmcnt(9)
	v_mfma_f32_16x16x32_bf16 v[126:129], v[218:221], v[66:69], v[126:129]
	ds_read_b128 v[218:221], v160 offset:8896
	s_waitcnt lgkmcnt(9)
	v_mfma_f32_16x16x32_bf16 v[122:125], v[234:237], v[70:73], v[122:125]
	s_waitcnt lgkmcnt(8)
	v_mfma_f32_16x16x32_bf16 v[126:129], v[238:241], v[70:73], v[126:129]
	s_waitcnt lgkmcnt(7)
	v_mfma_f32_16x16x32_bf16 v[122:125], v[242:245], v[74:77], v[122:125]
	s_waitcnt lgkmcnt(6)
	v_mfma_f32_16x16x32_bf16 v[126:129], v[246:249], v[74:77], v[126:129]
	s_waitcnt lgkmcnt(5)
	v_mfma_f32_16x16x32_bf16 v[122:125], v[162:165], v[78:81], v[122:125]
	s_waitcnt lgkmcnt(4)
	v_mfma_f32_16x16x32_bf16 v[126:129], v[200:203], v[78:81], v[126:129]
	s_waitcnt lgkmcnt(3)
	v_mfma_f32_16x16x32_bf16 v[122:125], v[204:207], v[86:89], v[122:125]
	s_waitcnt lgkmcnt(2)
	v_mfma_f32_16x16x32_bf16 v[126:129], v[208:211], v[86:89], v[126:129]
	s_waitcnt lgkmcnt(1)
	v_mfma_f32_16x16x32_bf16 v[122:125], v[214:217], v[94:97], v[122:125]
	s_waitcnt lgkmcnt(0)
	v_mfma_f32_16x16x32_bf16 v[126:129], v[218:221], v[94:97], v[126:129]
	s_cselect_b32 s3, 0, 0x4200
	s_add_i32 s11, s3, 0
	v_add_u32_e32 v162, s11, v157
	v_add_u32_e32 v161, s11, v158
	s_waitcnt vmcnt(9)
	ds_write_b128 v162, v[46:49]
	s_waitcnt vmcnt(8)
	ds_write_b128 v161, v[62:65]
	s_waitcnt lgkmcnt(0)
	s_barrier
	s_cmp_gt_u32 s1, 4
	s_cbranch_scc1 .LBB0_416
	v_lshl_add_u64 v[42:43], v[154:155], 0, s[4:5]
	v_lshl_add_u64 v[50:51], v[152:153], 0, s[4:5]
	global_load_dwordx4 v[42:45], v[42:43], off
	s_nop 0
	global_load_dwordx4 v[58:61], v[50:51], off
	v_lshl_add_u64 v[50:51], v[150:151], 0, s[4:5]
	v_add_co_u32_e32 v94, vcc, 0x1ca00000, v50
	s_nop 1
	v_addc_co_u32_e32 v95, vcc, 0, v51, vcc
	global_load_dwordx4 v[50:53], v[94:95], off offset:1536
	global_load_dwordx4 v[54:57], v[94:95], off offset:1600
	global_load_dwordx4 v[66:69], v[94:95], off offset:1664
	global_load_dwordx4 v[70:73], v[94:95], off offset:1728
	global_load_dwordx4 v[74:77], v[94:95], off offset:1792
	global_load_dwordx4 v[78:81], v[94:95], off offset:1856
	global_load_dwordx4 v[86:89], v[94:95], off offset:1920
	s_nop 0
	global_load_dwordx4 v[94:97], v[94:95], off offset:1984
.LBB0_416:
	v_add_u32_e32 v161, s3, v159
	ds_read_b128 v[162:165], v161
	ds_read_b128 v[200:203], v161 offset:8448
	ds_read_b128 v[204:207], v161 offset:64
	ds_read_b128 v[208:211], v161 offset:8512
	ds_read_b128 v[214:217], v161 offset:128
	ds_read_b128 v[218:221], v161 offset:8576
	ds_read_b128 v[234:237], v161 offset:192
	ds_read_b128 v[238:241], v161 offset:8640
	ds_read_b128 v[242:245], v161 offset:256
	ds_read_b128 v[246:249], v161 offset:8704
	s_waitcnt vmcnt(7) lgkmcnt(9)
	v_mfma_f32_16x16x32_bf16 v[122:125], v[162:165], v[82:85], v[122:125]
	ds_read_b128 v[162:165], v161 offset:320
	s_waitcnt lgkmcnt(9)
	v_mfma_f32_16x16x32_bf16 v[126:129], v[200:203], v[82:85], v[126:129]
	ds_read_b128 v[200:203], v161 offset:8768
	s_waitcnt vmcnt(6) lgkmcnt(9)
	v_mfma_f32_16x16x32_bf16 v[122:125], v[204:207], v[90:93], v[122:125]
	ds_read_b128 v[204:207], v161 offset:384
	s_waitcnt lgkmcnt(9)
	v_mfma_f32_16x16x32_bf16 v[126:129], v[208:211], v[90:93], v[126:129]
	ds_read_b128 v[208:211], v161 offset:8832
	s_waitcnt vmcnt(5) lgkmcnt(9)
	v_mfma_f32_16x16x32_bf16 v[122:125], v[214:217], v[98:101], v[122:125]
	ds_read_b128 v[214:217], v161 offset:448
	s_waitcnt lgkmcnt(9)
	v_mfma_f32_16x16x32_bf16 v[126:129], v[218:221], v[98:101], v[126:129]
	ds_read_b128 v[218:221], v161 offset:8896
	s_waitcnt vmcnt(4) lgkmcnt(9)
	v_mfma_f32_16x16x32_bf16 v[122:125], v[234:237], v[102:105], v[122:125]
	s_waitcnt lgkmcnt(8)
	v_mfma_f32_16x16x32_bf16 v[126:129], v[238:241], v[102:105], v[126:129]
	s_waitcnt vmcnt(3) lgkmcnt(7)
	v_mfma_f32_16x16x32_bf16 v[122:125], v[242:245], v[106:109], v[122:125]
	s_waitcnt lgkmcnt(6)
	v_mfma_f32_16x16x32_bf16 v[126:129], v[246:249], v[106:109], v[126:129]
	s_waitcnt vmcnt(2) lgkmcnt(5)
	v_mfma_f32_16x16x32_bf16 v[122:125], v[162:165], v[110:113], v[122:125]
	s_waitcnt lgkmcnt(4)
	v_mfma_f32_16x16x32_bf16 v[126:129], v[200:203], v[110:113], v[126:129]
	s_waitcnt vmcnt(1) lgkmcnt(3)
	v_mfma_f32_16x16x32_bf16 v[122:125], v[204:207], v[114:117], v[122:125]
	s_waitcnt lgkmcnt(2)
	v_mfma_f32_16x16x32_bf16 v[126:129], v[208:211], v[114:117], v[126:129]
	s_waitcnt vmcnt(0) lgkmcnt(1)
	v_mfma_f32_16x16x32_bf16 v[122:125], v[214:217], v[118:121], v[122:125]
	s_waitcnt lgkmcnt(0)
	v_mfma_f32_16x16x32_bf16 v[126:129], v[218:221], v[118:121], v[126:129]
	s_andn2_b64 vcc, exec, s[8:9]
	s_cbranch_vccnz .LBB0_418
	s_add_i32 s2, s2, 0
	v_add_u32_e32 v162, s2, v157
	v_add_u32_e32 v161, s2, v158
	ds_write_b128 v162, v[6:9]
	ds_write_b128 v161, v[2:5]

.LBB0_423:
	ds_read_b128 v[162:165], v160
	ds_read_b128 v[200:203], v160 offset:8448
	ds_read_b128 v[204:207], v160 offset:64
	ds_read_b128 v[208:211], v160 offset:8512
	ds_read_b128 v[214:217], v160 offset:128
	ds_read_b128 v[218:221], v160 offset:8576
	ds_read_b128 v[234:237], v160 offset:192
	ds_read_b128 v[238:241], v160 offset:8640
	ds_read_b128 v[242:245], v160 offset:256
	ds_read_b128 v[246:249], v160 offset:8704
	s_waitcnt lgkmcnt(9)
	v_mfma_f32_16x16x32_bf16 v[122:125], v[162:165], v[38:41], v[122:125]
	ds_read_b128 v[162:165], v160 offset:320
	s_waitcnt lgkmcnt(9)
	v_mfma_f32_16x16x32_bf16 v[126:129], v[200:203], v[38:41], v[126:129]
	ds_read_b128 v[200:203], v160 offset:8768
	s_waitcnt lgkmcnt(9)
	v_mfma_f32_16x16x32_bf16 v[122:125], v[204:207], v[34:37], v[122:125]
	ds_read_b128 v[204:207], v160 offset:384
	s_waitcnt lgkmcnt(9)
	v_mfma_f32_16x16x32_bf16 v[126:129], v[208:211], v[34:37], v[126:129]
	ds_read_b128 v[208:211], v160 offset:8832
	s_waitcnt lgkmcnt(9)
	v_mfma_f32_16x16x32_bf16 v[122:125], v[214:217], v[30:33], v[122:125]
	ds_read_b128 v[214:217], v160 offset:448
	s_waitcnt lgkmcnt(9)
	v_mfma_f32_16x16x32_bf16 v[126:129], v[218:221], v[30:33], v[126:129]
	s_waitcnt lgkmcnt(8)
	v_mfma_f32_16x16x32_bf16 v[122:125], v[234:237], v[26:29], v[122:125]
	s_waitcnt lgkmcnt(7)
	v_mfma_f32_16x16x32_bf16 v[126:129], v[238:241], v[26:29], v[126:129]
	s_waitcnt lgkmcnt(6)
	v_mfma_f32_16x16x32_bf16 v[122:125], v[242:245], v[22:25], v[122:125]
	s_waitcnt lgkmcnt(5)
	v_mfma_f32_16x16x32_bf16 v[126:129], v[246:249], v[22:25], v[126:129]
	s_waitcnt lgkmcnt(4)
	v_mfma_f32_16x16x32_bf16 v[122:125], v[162:165], v[18:21], v[122:125]
	s_waitcnt lgkmcnt(3)
	v_mfma_f32_16x16x32_bf16 v[126:129], v[200:203], v[18:21], v[126:129]
	s_waitcnt lgkmcnt(2)
	v_mfma_f32_16x16x32_bf16 v[122:125], v[204:207], v[14:17], v[122:125]
	s_waitcnt lgkmcnt(1)
	v_mfma_f32_16x16x32_bf16 v[126:129], v[208:211], v[14:17], v[126:129]
	s_waitcnt lgkmcnt(0)
	v_mfma_f32_16x16x32_bf16 v[122:125], v[214:217], v[10:13], v[122:125]
	ds_read_b128 v[160:163], v160 offset:8896
	s_waitcnt lgkmcnt(0)
	v_mfma_f32_16x16x32_bf16 v[126:129], v[160:163], v[10:13], v[126:129]
	s_add_i32 s1, s1, 3
	s_cmpk_eq_i32 s4, 0xa00
	s_cbranch_scc1 .LBB0_411
	s_bitcmp1_b32 s1, 0
	s_cselect_b32 s2, 0x4200, 0
	s_add_i32 s2, s2, 0
	v_add_u32_e32 v161, s2, v157
	v_add_u32_e32 v160, s2, v158
	ds_write_b128 v161, v[42:45]
	ds_write_b128 v160, v[58:61]
	s_branch .LBB0_411

.LBB0_1657:
	s_ashr_i32 s4, s16, 31
	s_lshr_b32 s4, s4, 26
	s_add_i32 s5, s16, s4
	s_ashr_i32 s4, s5, 6
	s_andn2_b32 s5, s5, 63
	v_or_b32_e32 v72, s5, v74
	s_mul_i32 s5, s4, 0xffcc0000
	s_add_i32 s5, s5, s12
	v_add_u32_e32 v2, s5, v78
	s_waitcnt lgkmcnt(0)
	v_ashrrev_i32_e32 v3, 31, v2
	v_lshl_add_u64 v[18:19], v[2:3], 1, v[64:65]
	v_add_u32_e32 v2, s5, v77
	v_ashrrev_i32_e32 v3, 31, v2
	v_lshl_add_u64 v[20:21], v[2:3], 1, v[66:67]
	v_add_u32_e32 v2, s5, v76
	v_ashrrev_i32_e32 v3, 31, v2
	v_lshl_add_u64 v[22:23], v[2:3], 1, v[68:69]
	v_add_u32_e32 v2, s5, v75
	s_movk_i32 s5, 0xd00
	v_ashrrev_i32_e32 v3, 31, v2
	v_mad_i64_i32 v[154:155], s[10:11], v72, s5, v[62:63]
	v_lshl_add_u64 v[24:25], v[2:3], 1, v[70:71]
	global_load_dwordx4 v[86:89], v[154:155], off
	global_load_dwordx4 v[90:93], v[154:155], off offset:64
	global_load_dwordx4 v[94:97], v[154:155], off offset:128
	global_load_dwordx4 v[98:101], v[154:155], off offset:192
	global_load_dwordx4 v[102:105], v[154:155], off offset:256
	global_load_dwordx4 v[106:109], v[154:155], off offset:320
	global_load_dwordx4 v[110:113], v[154:155], off offset:384
	global_load_dwordx4 v[114:117], v[154:155], off offset:448
	global_load_dwordx4 v[2:5], v[18:19], off
	global_load_dwordx4 v[118:121], v[18:19], off offset:512
	global_load_dwordx4 v[6:9], v[20:21], off
	global_load_dwordx4 v[122:125], v[20:21], off offset:512
	global_load_dwordx4 v[10:13], v[22:23], off
	global_load_dwordx4 v[126:129], v[22:23], off offset:512
	global_load_dwordx4 v[14:17], v[24:25], off
	global_load_dwordx4 v[130:133], v[24:25], off offset:512
	global_load_dwordx4 v[134:137], v[154:155], off offset:512
	global_load_dwordx4 v[138:141], v[154:155], off offset:576
	global_load_dwordx4 v[142:145], v[154:155], off offset:640
	global_load_dwordx4 v[146:149], v[154:155], off offset:704
	global_load_dwordx4 v[150:153], v[154:155], off offset:768
	global_load_dwordx4 v[58:61], v[154:155], off offset:832
	global_load_dwordx4 v[54:57], v[154:155], off offset:896
	global_load_dwordx4 v[30:33], v[154:155], off offset:960
	s_waitcnt vmcnt(15)
	ds_write_b128 v80, v[2:5]
	s_waitcnt vmcnt(13)
	ds_write_b128 v81, v[6:9]
	s_waitcnt vmcnt(11)
	ds_write_b128 v82, v[10:13]
	s_waitcnt vmcnt(9)
	ds_write_b128 v83, v[14:17]
	s_waitcnt lgkmcnt(0)
	s_barrier
	global_load_dwordx4 v[38:41], v[18:19], off offset:1024
	global_load_dwordx4 v[42:45], v[20:21], off offset:1024
	global_load_dwordx4 v[46:49], v[22:23], off offset:1024
	global_load_dwordx4 v[50:53], v[24:25], off offset:1024
	global_load_dwordx4 v[34:37], v[154:155], off offset:1024
	global_load_dwordx4 v[26:29], v[154:155], off offset:1088
	s_nop 0
	global_load_dwordx4 v[22:25], v[154:155], off offset:1152
	global_load_dwordx4 v[18:21], v[154:155], off offset:1216
	global_load_dwordx4 v[14:17], v[154:155], off offset:1280
	global_load_dwordx4 v[10:13], v[154:155], off offset:1344
	global_load_dwordx4 v[6:9], v[154:155], off offset:1408
	global_load_dwordx4 v[2:5], v[154:155], off offset:1472
	ds_read_b128 v[154:157], v84
	ds_read_b128 v[158:161], v84 offset:8448
	s_waitcnt lgkmcnt(1)
	v_mfma_f32_16x16x32_bf16 v[154:157], v[154:157], v[86:89], 0
	s_waitcnt lgkmcnt(0)
	v_mfma_f32_16x16x32_bf16 v[86:89], v[158:161], v[86:89], 0
	ds_read_b128 v[158:161], v84 offset:64
	s_waitcnt lgkmcnt(0)
	v_mfma_f32_16x16x32_bf16 v[154:157], v[158:161], v[90:93], v[154:157]
	ds_read_b128 v[158:161], v84 offset:8512
	s_waitcnt lgkmcnt(0)
	v_mfma_f32_16x16x32_bf16 v[86:89], v[158:161], v[90:93], v[86:89]
	ds_read_b128 v[90:93], v84 offset:128
	s_waitcnt lgkmcnt(0)
	v_mfma_f32_16x16x32_bf16 v[90:93], v[90:93], v[94:97], v[154:157]
	s_nop 2
	ds_read_b128 v[154:157], v84 offset:8576
	s_waitcnt lgkmcnt(0)
	v_mfma_f32_16x16x32_bf16 v[86:89], v[154:157], v[94:97], v[86:89]
	ds_read_b128 v[94:97], v84 offset:192
	ds_read_b128 v[200:203], v84 offset:8640
	ds_read_b128 v[204:207], v84 offset:256
	ds_read_b128 v[208:211], v84 offset:8704
	ds_read_b128 v[214:217], v84 offset:320
	ds_read_b128 v[218:221], v84 offset:8768
	ds_read_b128 v[234:237], v84 offset:384
	ds_read_b128 v[238:241], v84 offset:8832
	ds_read_b128 v[242:245], v84 offset:448
	ds_read_b128 v[246:249], v84 offset:8896
	s_waitcnt lgkmcnt(9)
	v_mfma_f32_16x16x32_bf16 v[90:93], v[94:97], v[98:101], v[90:93]
	s_waitcnt lgkmcnt(8)
	v_mfma_f32_16x16x32_bf16 v[86:89], v[200:203], v[98:101], v[86:89]
	s_waitcnt lgkmcnt(7)
	v_mfma_f32_16x16x32_bf16 v[90:93], v[204:207], v[102:105], v[90:93]
	s_waitcnt lgkmcnt(6)
	v_mfma_f32_16x16x32_bf16 v[86:89], v[208:211], v[102:105], v[86:89]
	s_waitcnt lgkmcnt(5)
	v_mfma_f32_16x16x32_bf16 v[90:93], v[214:217], v[106:109], v[90:93]
	s_waitcnt lgkmcnt(4)
	v_mfma_f32_16x16x32_bf16 v[86:89], v[218:221], v[106:109], v[86:89]
	s_waitcnt lgkmcnt(3)
	v_mfma_f32_16x16x32_bf16 v[90:93], v[234:237], v[110:113], v[90:93]
	s_waitcnt lgkmcnt(2)
	v_mfma_f32_16x16x32_bf16 v[86:89], v[238:241], v[110:113], v[86:89]
	s_waitcnt lgkmcnt(1)
	v_mfma_f32_16x16x32_bf16 v[90:93], v[242:245], v[114:117], v[90:93]
	s_waitcnt lgkmcnt(0)
	v_mfma_f32_16x16x32_bf16 v[86:89], v[246:249], v[114:117], v[86:89]
	ds_write_b128 v80, v[118:121] offset:33792
	ds_write_b128 v81, v[122:125] offset:33792
	ds_write_b128 v82, v[126:129] offset:33792
	s_waitcnt vmcnt(20)
	ds_write_b128 v83, v[130:133] offset:33792
	s_waitcnt lgkmcnt(0)
	s_barrier
	ds_read_b128 v[94:97], v84 offset:33792
	ds_read_b128 v[200:203], v84 offset:42240
	ds_read_b128 v[204:207], v84 offset:33856
	ds_read_b128 v[208:211], v84 offset:42304
	ds_read_b128 v[214:217], v84 offset:33920
	ds_read_b128 v[218:221], v84 offset:42368
	ds_read_b128 v[234:237], v84 offset:33984
	ds_read_b128 v[238:241], v84 offset:42432
	ds_read_b128 v[242:245], v84 offset:34048
	ds_read_b128 v[246:249], v84 offset:42496
	s_waitcnt vmcnt(19) lgkmcnt(9)
	v_mfma_f32_16x16x32_bf16 v[90:93], v[94:97], v[134:137], v[90:93]
	ds_read_b128 v[94:97], v84 offset:34112
	s_waitcnt lgkmcnt(9)
	v_mfma_f32_16x16x32_bf16 v[86:89], v[200:203], v[134:137], v[86:89]
	ds_read_b128 v[200:203], v84 offset:42560
	s_waitcnt vmcnt(18) lgkmcnt(9)
	v_mfma_f32_16x16x32_bf16 v[90:93], v[204:207], v[138:141], v[90:93]
	s_waitcnt lgkmcnt(8)
	v_mfma_f32_16x16x32_bf16 v[86:89], v[208:211], v[138:141], v[86:89]
	s_waitcnt vmcnt(17) lgkmcnt(7)
	v_mfma_f32_16x16x32_bf16 v[90:93], v[214:217], v[142:145], v[90:93]
	s_waitcnt lgkmcnt(6)
	v_mfma_f32_16x16x32_bf16 v[86:89], v[218:221], v[142:145], v[86:89]
	s_waitcnt vmcnt(16) lgkmcnt(5)
	v_mfma_f32_16x16x32_bf16 v[90:93], v[234:237], v[146:149], v[90:93]
	s_waitcnt lgkmcnt(4)
	v_mfma_f32_16x16x32_bf16 v[86:89], v[238:241], v[146:149], v[86:89]
	s_waitcnt vmcnt(15) lgkmcnt(3)
	v_mfma_f32_16x16x32_bf16 v[90:93], v[242:245], v[150:153], v[90:93]
	s_waitcnt lgkmcnt(2)
	v_mfma_f32_16x16x32_bf16 v[86:89], v[246:249], v[150:153], v[86:89]
	s_waitcnt vmcnt(14) lgkmcnt(1)
	v_mfma_f32_16x16x32_bf16 v[90:93], v[94:97], v[58:61], v[90:93]
	s_waitcnt lgkmcnt(0)
	v_mfma_f32_16x16x32_bf16 v[58:61], v[200:203], v[58:61], v[86:89]
	s_nop 2
	ds_read_b128 v[86:89], v84 offset:34176
	s_waitcnt vmcnt(13) lgkmcnt(0)
	v_mfma_f32_16x16x32_bf16 v[86:89], v[86:89], v[54:57], v[90:93]
	s_nop 2
	ds_read_b128 v[90:93], v84 offset:42624
	s_waitcnt lgkmcnt(0)
	v_mfma_f32_16x16x32_bf16 v[54:57], v[90:93], v[54:57], v[58:61]
	s_nop 2
	ds_read_b128 v[58:61], v84 offset:34240
	s_waitcnt vmcnt(12) lgkmcnt(0)
	v_mfma_f32_16x16x32_bf16 v[58:61], v[58:61], v[30:33], v[86:89]
	s_nop 2
	ds_read_b128 v[86:89], v84 offset:42688
	s_waitcnt lgkmcnt(0)
	v_mfma_f32_16x16x32_bf16 v[30:33], v[86:89], v[30:33], v[54:57]
	s_waitcnt vmcnt(11)
	ds_write_b128 v80, v[38:41]
	s_waitcnt vmcnt(10)
	ds_write_b128 v81, v[42:45]
	s_waitcnt vmcnt(9)
	ds_write_b128 v82, v[46:49]
	s_waitcnt vmcnt(8)
	ds_write_b128 v83, v[50:53]
	s_waitcnt lgkmcnt(0)
	s_barrier
	ds_read_b128 v[38:41], v84
	ds_read_b128 v[42:45], v84 offset:8448
	s_waitcnt vmcnt(7) lgkmcnt(1)
	v_mfma_f32_16x16x32_bf16 v[38:41], v[38:41], v[34:37], v[58:61]
	s_waitcnt lgkmcnt(0)
	v_mfma_f32_16x16x32_bf16 v[30:33], v[42:45], v[34:37], v[30:33]
	ds_read_b128 v[34:37], v84 offset:64
	s_waitcnt vmcnt(6) lgkmcnt(0)
	v_mfma_f32_16x16x32_bf16 v[34:37], v[34:37], v[26:29], v[38:41]
	s_nop 2
	ds_read_b128 v[38:41], v84 offset:8512
	s_waitcnt lgkmcnt(0)
	v_mfma_f32_16x16x32_bf16 v[26:29], v[38:41], v[26:29], v[30:33]
	s_nop 2
	ds_read_b128 v[30:33], v84 offset:128
	s_waitcnt vmcnt(5) lgkmcnt(0)
	v_mfma_f32_16x16x32_bf16 v[30:33], v[30:33], v[22:25], v[34:37]
	s_nop 2
	ds_read_b128 v[34:37], v84 offset:8576
	s_waitcnt lgkmcnt(0)
	v_mfma_f32_16x16x32_bf16 v[22:25], v[34:37], v[22:25], v[26:29]
	s_nop 2
	ds_read_b128 v[26:29], v84 offset:192
	s_waitcnt vmcnt(4) lgkmcnt(0)
	v_mfma_f32_16x16x32_bf16 v[26:29], v[26:29], v[18:21], v[30:33]
	s_nop 2
	ds_read_b128 v[30:33], v84 offset:8640
	s_waitcnt lgkmcnt(0)
	v_mfma_f32_16x16x32_bf16 v[18:21], v[30:33], v[18:21], v[22:25]
	s_nop 2
	ds_read_b128 v[22:25], v84 offset:256
	s_waitcnt vmcnt(3) lgkmcnt(0)
	v_mfma_f32_16x16x32_bf16 v[22:25], v[22:25], v[14:17], v[26:29]
	s_nop 2
	ds_read_b128 v[26:29], v84 offset:8704
	s_waitcnt lgkmcnt(0)
	v_mfma_f32_16x16x32_bf16 v[14:17], v[26:29], v[14:17], v[18:21]
	s_nop 2
	ds_read_b128 v[18:21], v84 offset:320
	s_waitcnt vmcnt(2) lgkmcnt(0)
	v_mfma_f32_16x16x32_bf16 v[18:21], v[18:21], v[10:13], v[22:25]
	s_nop 2
	ds_read_b128 v[22:25], v84 offset:8768
	s_waitcnt lgkmcnt(0)
	v_mfma_f32_16x16x32_bf16 v[10:13], v[22:25], v[10:13], v[14:17]
	s_nop 2
	ds_read_b128 v[14:17], v84 offset:384
	s_waitcnt vmcnt(1) lgkmcnt(0)
	v_mfma_f32_16x16x32_bf16 v[14:17], v[14:17], v[6:9], v[18:21]
	s_nop 2
	ds_read_b128 v[18:21], v84 offset:8832
	s_waitcnt lgkmcnt(0)
	v_mfma_f32_16x16x32_bf16 v[10:13], v[18:21], v[6:9], v[10:13]
	ds_read_b128 v[6:9], v84 offset:448
	s_waitcnt vmcnt(0) lgkmcnt(0)
	v_mfma_f32_16x16x32_bf16 v[6:9], v[6:9], v[2:5], v[14:17]
	s_nop 2
	ds_read_b128 v[14:17], v84 offset:8896
	s_waitcnt lgkmcnt(0)
	v_mfma_f32_16x16x32_bf16 v[2:5], v[14:17], v[2:5], v[10:13]
	s_waitcnt lgkmcnt(0)
	s_barrier
	s_andn2_b64 vcc, exec, s[6:7]
	s_cbranch_vccnz .LBB0_1659
	s_nop 0
	v_add_u32_e32 v10, s2, v0
	ds_write_b128 v10, v[6:9]
	s_nop 2
	ds_write_b128 v10, v[2:5] offset:1024

.LBB0_1757:
	s_bitcmp1_b32 s18, 0
	s_cselect_b32 s2, 0x8400, 0
	v_add_u32_e32 v0, s2, v239
	ds_read_b128 v[194:197], v0
	ds_read_b128 v[234:237], v0 offset:8448
	s_waitcnt lgkmcnt(1)
	v_mfma_f32_16x16x32_bf16 v[146:149], v[194:197], v[66:69], v[146:149]
	ds_read_b128 v[194:197], v0 offset:16896
	s_waitcnt lgkmcnt(1)
	v_mfma_f32_16x16x32_bf16 v[150:153], v[234:237], v[66:69], v[150:153]
	ds_read_b128 v[234:237], v0 offset:25344
	s_waitcnt lgkmcnt(1)
	v_mfma_f32_16x16x32_bf16 v[158:161], v[194:197], v[66:69], v[158:161]
	ds_read_b128 v[194:197], v0 offset:64
	s_waitcnt lgkmcnt(1)
	v_mfma_f32_16x16x32_bf16 v[154:157], v[234:237], v[66:69], v[154:157]
	ds_read_b128 v[234:237], v0 offset:8512
	s_waitcnt lgkmcnt(1)
	v_mfma_f32_16x16x32_bf16 v[146:149], v[194:197], v[70:73], v[146:149]
	ds_read_b128 v[194:197], v0 offset:16960
	s_waitcnt lgkmcnt(1)
	v_mfma_f32_16x16x32_bf16 v[150:153], v[234:237], v[70:73], v[150:153]
	ds_read_b128 v[234:237], v0 offset:25408
	s_waitcnt lgkmcnt(1)
	v_mfma_f32_16x16x32_bf16 v[158:161], v[194:197], v[70:73], v[158:161]
	ds_read_b128 v[194:197], v0 offset:128
	s_waitcnt lgkmcnt(1)
	v_mfma_f32_16x16x32_bf16 v[154:157], v[234:237], v[70:73], v[154:157]
	ds_read_b128 v[234:237], v0 offset:8576
	s_waitcnt lgkmcnt(1)
	v_mfma_f32_16x16x32_bf16 v[146:149], v[194:197], v[82:85], v[146:149]
	ds_read_b128 v[194:197], v0 offset:17024
	s_waitcnt lgkmcnt(1)
	v_mfma_f32_16x16x32_bf16 v[150:153], v[234:237], v[82:85], v[150:153]
	ds_read_b128 v[234:237], v0 offset:25472
	s_waitcnt lgkmcnt(1)
	v_mfma_f32_16x16x32_bf16 v[158:161], v[194:197], v[82:85], v[158:161]
	ds_read_b128 v[194:197], v0 offset:192
	s_waitcnt lgkmcnt(1)
	v_mfma_f32_16x16x32_bf16 v[154:157], v[234:237], v[82:85], v[154:157]
	ds_read_b128 v[234:237], v0 offset:8640
	s_waitcnt lgkmcnt(1)
	v_mfma_f32_16x16x32_bf16 v[146:149], v[194:197], v[86:89], v[146:149]
	ds_read_b128 v[194:197], v0 offset:17088
	s_waitcnt lgkmcnt(1)
	v_mfma_f32_16x16x32_bf16 v[150:153], v[234:237], v[86:89], v[150:153]
	ds_read_b128 v[234:237], v0 offset:25536
	s_waitcnt lgkmcnt(1)
	v_mfma_f32_16x16x32_bf16 v[158:161], v[194:197], v[86:89], v[158:161]
	ds_read_b128 v[194:197], v0 offset:256
	s_waitcnt lgkmcnt(1)
	v_mfma_f32_16x16x32_bf16 v[154:157], v[234:237], v[86:89], v[154:157]
	ds_read_b128 v[234:237], v0 offset:8704
	s_waitcnt lgkmcnt(1)
	v_mfma_f32_16x16x32_bf16 v[146:149], v[194:197], v[98:101], v[146:149]
	ds_read_b128 v[194:197], v0 offset:17152
	s_waitcnt lgkmcnt(1)
	v_mfma_f32_16x16x32_bf16 v[150:153], v[234:237], v[98:101], v[150:153]
	ds_read_b128 v[234:237], v0 offset:25600
	s_waitcnt lgkmcnt(1)
	v_mfma_f32_16x16x32_bf16 v[158:161], v[194:197], v[98:101], v[158:161]
	ds_read_b128 v[194:197], v0 offset:320
	s_waitcnt lgkmcnt(1)
	v_mfma_f32_16x16x32_bf16 v[154:157], v[234:237], v[98:101], v[154:157]
	ds_read_b128 v[234:237], v0 offset:8768
	s_waitcnt lgkmcnt(1)
	v_mfma_f32_16x16x32_bf16 v[146:149], v[194:197], v[102:105], v[146:149]
	ds_read_b128 v[194:197], v0 offset:17216
	s_waitcnt lgkmcnt(1)
	v_mfma_f32_16x16x32_bf16 v[150:153], v[234:237], v[102:105], v[150:153]
	ds_read_b128 v[234:237], v0 offset:25664
	s_waitcnt lgkmcnt(1)
	v_mfma_f32_16x16x32_bf16 v[158:161], v[194:197], v[102:105], v[158:161]
	ds_read_b128 v[194:197], v0 offset:384
	s_waitcnt lgkmcnt(1)
	v_mfma_f32_16x16x32_bf16 v[154:157], v[234:237], v[102:105], v[154:157]
	ds_read_b128 v[234:237], v0 offset:8832
	s_waitcnt lgkmcnt(1)
	v_mfma_f32_16x16x32_bf16 v[146:149], v[194:197], v[106:109], v[146:149]
	ds_read_b128 v[194:197], v0 offset:17280
	s_waitcnt lgkmcnt(1)
	v_mfma_f32_16x16x32_bf16 v[150:153], v[234:237], v[106:109], v[150:153]
	ds_read_b128 v[234:237], v0 offset:25728
	s_waitcnt lgkmcnt(1)
	v_mfma_f32_16x16x32_bf16 v[158:161], v[194:197], v[106:109], v[158:161]
	s_waitcnt lgkmcnt(0)
	v_mfma_f32_16x16x32_bf16 v[194:197], v[234:237], v[106:109], v[154:157]
	s_nop 2
	ds_read_b128 v[154:157], v0 offset:448
	s_waitcnt lgkmcnt(0)
	v_mfma_f32_16x16x32_bf16 v[146:149], v[154:157], v[110:113], v[146:149]
	ds_read_b128 v[154:157], v0 offset:8896
	s_waitcnt lgkmcnt(0)
	v_mfma_f32_16x16x32_bf16 v[150:153], v[154:157], v[110:113], v[150:153]
	ds_read_b128 v[154:157], v0 offset:17344
	s_waitcnt lgkmcnt(0)
	v_mfma_f32_16x16x32_bf16 v[154:157], v[154:157], v[110:113], v[158:161]
	s_nop 2
	ds_read_b128 v[158:161], v0 offset:25792
	s_waitcnt lgkmcnt(0)
	v_mfma_f32_16x16x32_bf16 v[158:161], v[158:161], v[110:113], v[194:197]
	s_cselect_b32 s3, 0, 0x8400
	s_add_i32 s19, s3, 0
	s_nop 0
	v_add_u32_e32 v197, s19, v179
	v_add_u32_e32 v194, s19, v225
	v_add_u32_e32 v195, s19, v223
	v_add_u32_e32 v196, s19, v221
	s_waitcnt vmcnt(11)
	ds_write_b128 v197, v[54:57]
	s_waitcnt vmcnt(10)
	ds_write_b128 v196, v[62:65]
	s_waitcnt vmcnt(9)
	ds_write_b128 v195, v[78:81]
	s_waitcnt vmcnt(8)
	ds_write_b128 v194, v[94:97]
	s_waitcnt lgkmcnt(0)
	s_barrier
	s_cmp_gt_u32 s18, 4
	s_cbranch_scc1 .LBB0_1759
	v_lshl_add_u64 v[50:51], v[218:219], 0, s[0:1]
	v_lshl_add_u64 v[58:59], v[216:217], 0, s[0:1]
	v_lshl_add_u64 v[66:67], v[214:215], 0, s[0:1]
	global_load_dwordx4 v[50:53], v[50:51], off
	s_nop 0
	global_load_dwordx4 v[58:61], v[58:59], off
	v_lshl_add_u64 v[68:69], v[212:213], 0, s[0:1]
	global_load_dwordx4 v[74:77], v[66:67], off
	global_load_dwordx4 v[90:93], v[68:69], off
	v_lshl_add_u64 v[66:67], v[210:211], 0, s[0:1]
	v_add_co_u32_e32 v110, vcc, 0x1ca00000, v66
	s_nop 1
	v_addc_co_u32_e32 v111, vcc, 0, v67, vcc
	global_load_dwordx4 v[66:69], v[110:111], off offset:1536
	global_load_dwordx4 v[70:73], v[110:111], off offset:1600
	global_load_dwordx4 v[82:85], v[110:111], off offset:1664
	global_load_dwordx4 v[86:89], v[110:111], off offset:1728
	global_load_dwordx4 v[98:101], v[110:111], off offset:1792
	global_load_dwordx4 v[102:105], v[110:111], off offset:1856
	global_load_dwordx4 v[106:109], v[110:111], off offset:1920
	s_nop 0
	global_load_dwordx4 v[110:113], v[110:111], off offset:1984
.LBB0_1759:
	v_add_u32_e32 v198, s3, v239
	ds_read_b128 v[194:197], v198
	ds_read_b128 v[234:237], v198 offset:8448
	s_waitcnt vmcnt(7) lgkmcnt(1)
	v_mfma_f32_16x16x32_bf16 v[146:149], v[194:197], v[114:117], v[146:149]
	ds_read_b128 v[194:197], v198 offset:16896
	s_waitcnt lgkmcnt(1)
	v_mfma_f32_16x16x32_bf16 v[150:153], v[234:237], v[114:117], v[150:153]
	ds_read_b128 v[234:237], v198 offset:25344
	s_waitcnt lgkmcnt(1)
	v_mfma_f32_16x16x32_bf16 v[154:157], v[194:197], v[114:117], v[154:157]
	ds_read_b128 v[194:197], v198 offset:64
	s_waitcnt lgkmcnt(1)
	v_mfma_f32_16x16x32_bf16 v[158:161], v[234:237], v[114:117], v[158:161]
	ds_read_b128 v[234:237], v198 offset:8512
	s_waitcnt vmcnt(6) lgkmcnt(1)
	v_mfma_f32_16x16x32_bf16 v[146:149], v[194:197], v[118:121], v[146:149]
	ds_read_b128 v[194:197], v198 offset:16960
	s_waitcnt lgkmcnt(1)
	v_mfma_f32_16x16x32_bf16 v[150:153], v[234:237], v[118:121], v[150:153]
	ds_read_b128 v[234:237], v198 offset:25408
	s_waitcnt lgkmcnt(1)
	v_mfma_f32_16x16x32_bf16 v[154:157], v[194:197], v[118:121], v[154:157]
	ds_read_b128 v[194:197], v198 offset:128
	s_waitcnt lgkmcnt(1)
	v_mfma_f32_16x16x32_bf16 v[158:161], v[234:237], v[118:121], v[158:161]
	ds_read_b128 v[234:237], v198 offset:8576
	s_waitcnt vmcnt(5) lgkmcnt(1)
	v_mfma_f32_16x16x32_bf16 v[146:149], v[194:197], v[122:125], v[146:149]
	ds_read_b128 v[194:197], v198 offset:17024
	s_waitcnt lgkmcnt(1)
	v_mfma_f32_16x16x32_bf16 v[150:153], v[234:237], v[122:125], v[150:153]
	ds_read_b128 v[234:237], v198 offset:25472
	s_waitcnt lgkmcnt(1)
	v_mfma_f32_16x16x32_bf16 v[154:157], v[194:197], v[122:125], v[154:157]
	ds_read_b128 v[194:197], v198 offset:192
	s_waitcnt lgkmcnt(1)
	v_mfma_f32_16x16x32_bf16 v[158:161], v[234:237], v[122:125], v[158:161]
	ds_read_b128 v[234:237], v198 offset:8640
	s_waitcnt vmcnt(4) lgkmcnt(1)
	v_mfma_f32_16x16x32_bf16 v[146:149], v[194:197], v[126:129], v[146:149]
	ds_read_b128 v[194:197], v198 offset:17088
	s_waitcnt lgkmcnt(1)
	v_mfma_f32_16x16x32_bf16 v[150:153], v[234:237], v[126:129], v[150:153]
	ds_read_b128 v[234:237], v198 offset:25536
	s_waitcnt lgkmcnt(1)
	v_mfma_f32_16x16x32_bf16 v[154:157], v[194:197], v[126:129], v[154:157]
	ds_read_b128 v[194:197], v198 offset:256
	s_waitcnt lgkmcnt(1)
	v_mfma_f32_16x16x32_bf16 v[158:161], v[234:237], v[126:129], v[158:161]
	ds_read_b128 v[234:237], v198 offset:8704
	s_waitcnt vmcnt(3) lgkmcnt(1)
	v_mfma_f32_16x16x32_bf16 v[146:149], v[194:197], v[130:133], v[146:149]
	ds_read_b128 v[194:197], v198 offset:17152
	s_waitcnt lgkmcnt(1)
	v_mfma_f32_16x16x32_bf16 v[150:153], v[234:237], v[130:133], v[150:153]
	ds_read_b128 v[234:237], v198 offset:25600
	s_waitcnt lgkmcnt(1)
	v_mfma_f32_16x16x32_bf16 v[154:157], v[194:197], v[130:133], v[154:157]
	ds_read_b128 v[194:197], v198 offset:320
	s_waitcnt lgkmcnt(1)
	v_mfma_f32_16x16x32_bf16 v[158:161], v[234:237], v[130:133], v[158:161]
	ds_read_b128 v[234:237], v198 offset:8768
	s_waitcnt vmcnt(2) lgkmcnt(1)
	v_mfma_f32_16x16x32_bf16 v[146:149], v[194:197], v[134:137], v[146:149]
	ds_read_b128 v[194:197], v198 offset:17216
	s_waitcnt lgkmcnt(1)
	v_mfma_f32_16x16x32_bf16 v[150:153], v[234:237], v[134:137], v[150:153]
	ds_read_b128 v[234:237], v198 offset:25664
	s_waitcnt lgkmcnt(1)
	v_mfma_f32_16x16x32_bf16 v[154:157], v[194:197], v[134:137], v[154:157]
	ds_read_b128 v[194:197], v198 offset:384
	s_waitcnt lgkmcnt(1)
	v_mfma_f32_16x16x32_bf16 v[158:161], v[234:237], v[134:137], v[158:161]
	ds_read_b128 v[234:237], v198 offset:8832
	s_waitcnt vmcnt(1) lgkmcnt(1)
	v_mfma_f32_16x16x32_bf16 v[146:149], v[194:197], v[138:141], v[146:149]
	ds_read_b128 v[194:197], v198 offset:17280
	s_waitcnt lgkmcnt(1)
	v_mfma_f32_16x16x32_bf16 v[150:153], v[234:237], v[138:141], v[150:153]
	ds_read_b128 v[234:237], v198 offset:25728
	s_waitcnt lgkmcnt(1)
	v_mfma_f32_16x16x32_bf16 v[154:157], v[194:197], v[138:141], v[154:157]
	s_waitcnt lgkmcnt(0)
	v_mfma_f32_16x16x32_bf16 v[194:197], v[234:237], v[138:141], v[158:161]
	s_nop 2
	ds_read_b128 v[158:161], v198 offset:448
	s_waitcnt vmcnt(0) lgkmcnt(0)
	v_mfma_f32_16x16x32_bf16 v[146:149], v[158:161], v[142:145], v[146:149]
	ds_read_b128 v[158:161], v198 offset:8896
	s_waitcnt lgkmcnt(0)
	v_mfma_f32_16x16x32_bf16 v[150:153], v[158:161], v[142:145], v[150:153]
	ds_read_b128 v[158:161], v198 offset:17344
	s_waitcnt lgkmcnt(0)
	v_mfma_f32_16x16x32_bf16 v[158:161], v[158:161], v[142:145], v[154:157]
	s_nop 2
	ds_read_b128 v[154:157], v198 offset:25792
	s_waitcnt lgkmcnt(0)
	v_mfma_f32_16x16x32_bf16 v[154:157], v[154:157], v[142:145], v[194:197]
	s_andn2_b64 vcc, exec, s[10:11]
	s_cbranch_vccnz .LBB0_1761
	s_add_i32 s2, s2, 0
	v_add_u32_e32 v197, s2, v179
	v_add_u32_e32 v194, s2, v225
	v_add_u32_e32 v195, s2, v223
	v_add_u32_e32 v196, s2, v221
	ds_write_b128 v197, v[6:9]
	ds_write_b128 v196, v[2:5]
	ds_write_b128 v195, v[14:17]
	ds_write_b128 v194, v[10:13]

.LBB0_1766:
	ds_read_b128 v[194:197], v0
	ds_read_b128 v[234:237], v0 offset:8448
	s_waitcnt lgkmcnt(1)
	v_mfma_f32_16x16x32_bf16 v[146:149], v[194:197], v[46:49], v[146:149]
	ds_read_b128 v[194:197], v0 offset:16896
	s_waitcnt lgkmcnt(1)
	v_mfma_f32_16x16x32_bf16 v[150:153], v[234:237], v[46:49], v[150:153]
	ds_read_b128 v[234:237], v0 offset:25344
	s_waitcnt lgkmcnt(1)
	v_mfma_f32_16x16x32_bf16 v[158:161], v[194:197], v[46:49], v[158:161]
	ds_read_b128 v[194:197], v0 offset:64
	s_waitcnt lgkmcnt(1)
	v_mfma_f32_16x16x32_bf16 v[154:157], v[234:237], v[46:49], v[154:157]
	ds_read_b128 v[234:237], v0 offset:8512
	s_waitcnt lgkmcnt(1)
	v_mfma_f32_16x16x32_bf16 v[146:149], v[194:197], v[42:45], v[146:149]
	ds_read_b128 v[194:197], v0 offset:16960
	s_waitcnt lgkmcnt(1)
	v_mfma_f32_16x16x32_bf16 v[150:153], v[234:237], v[42:45], v[150:153]
	ds_read_b128 v[234:237], v0 offset:25408
	s_waitcnt lgkmcnt(1)
	v_mfma_f32_16x16x32_bf16 v[158:161], v[194:197], v[42:45], v[158:161]
	ds_read_b128 v[194:197], v0 offset:128
	s_waitcnt lgkmcnt(1)
	v_mfma_f32_16x16x32_bf16 v[154:157], v[234:237], v[42:45], v[154:157]
	ds_read_b128 v[234:237], v0 offset:8576
	s_waitcnt lgkmcnt(1)
	v_mfma_f32_16x16x32_bf16 v[146:149], v[194:197], v[38:41], v[146:149]
	ds_read_b128 v[194:197], v0 offset:17024
	s_waitcnt lgkmcnt(1)
	v_mfma_f32_16x16x32_bf16 v[150:153], v[234:237], v[38:41], v[150:153]
	ds_read_b128 v[234:237], v0 offset:25472
	s_waitcnt lgkmcnt(1)
	v_mfma_f32_16x16x32_bf16 v[158:161], v[194:197], v[38:41], v[158:161]
	ds_read_b128 v[194:197], v0 offset:192
	s_waitcnt lgkmcnt(1)
	v_mfma_f32_16x16x32_bf16 v[154:157], v[234:237], v[38:41], v[154:157]
	ds_read_b128 v[234:237], v0 offset:8640
	s_waitcnt lgkmcnt(1)
	v_mfma_f32_16x16x32_bf16 v[146:149], v[194:197], v[34:37], v[146:149]
	ds_read_b128 v[194:197], v0 offset:17088
	s_waitcnt lgkmcnt(1)
	v_mfma_f32_16x16x32_bf16 v[150:153], v[234:237], v[34:37], v[150:153]
	ds_read_b128 v[234:237], v0 offset:25536
	s_waitcnt lgkmcnt(1)
	v_mfma_f32_16x16x32_bf16 v[158:161], v[194:197], v[34:37], v[158:161]
	ds_read_b128 v[194:197], v0 offset:256
	s_waitcnt lgkmcnt(1)
	v_mfma_f32_16x16x32_bf16 v[154:157], v[234:237], v[34:37], v[154:157]
	ds_read_b128 v[234:237], v0 offset:8704
	s_waitcnt lgkmcnt(1)
	v_mfma_f32_16x16x32_bf16 v[146:149], v[194:197], v[30:33], v[146:149]
	ds_read_b128 v[194:197], v0 offset:17152
	s_waitcnt lgkmcnt(1)
	v_mfma_f32_16x16x32_bf16 v[150:153], v[234:237], v[30:33], v[150:153]
	ds_read_b128 v[234:237], v0 offset:25600
	s_waitcnt lgkmcnt(1)
	v_mfma_f32_16x16x32_bf16 v[158:161], v[194:197], v[30:33], v[158:161]
	ds_read_b128 v[194:197], v0 offset:320
	s_waitcnt lgkmcnt(1)
	v_mfma_f32_16x16x32_bf16 v[154:157], v[234:237], v[30:33], v[154:157]
	ds_read_b128 v[234:237], v0 offset:8768
	s_waitcnt lgkmcnt(1)
	v_mfma_f32_16x16x32_bf16 v[146:149], v[194:197], v[26:29], v[146:149]
	ds_read_b128 v[194:197], v0 offset:17216
	s_waitcnt lgkmcnt(1)
	v_mfma_f32_16x16x32_bf16 v[150:153], v[234:237], v[26:29], v[150:153]
	ds_read_b128 v[234:237], v0 offset:25664
	s_waitcnt lgkmcnt(1)
	v_mfma_f32_16x16x32_bf16 v[158:161], v[194:197], v[26:29], v[158:161]
	ds_read_b128 v[194:197], v0 offset:384
	s_waitcnt lgkmcnt(1)
	v_mfma_f32_16x16x32_bf16 v[154:157], v[234:237], v[26:29], v[154:157]
	ds_read_b128 v[234:237], v0 offset:8832
	s_waitcnt lgkmcnt(1)
	v_mfma_f32_16x16x32_bf16 v[146:149], v[194:197], v[22:25], v[146:149]
	ds_read_b128 v[194:197], v0 offset:17280
	s_waitcnt lgkmcnt(1)
	v_mfma_f32_16x16x32_bf16 v[150:153], v[234:237], v[22:25], v[150:153]
	ds_read_b128 v[234:237], v0 offset:25728
	s_waitcnt lgkmcnt(1)
	v_mfma_f32_16x16x32_bf16 v[158:161], v[194:197], v[22:25], v[158:161]
	ds_read_b128 v[194:197], v0 offset:448
	s_waitcnt lgkmcnt(1)
	v_mfma_f32_16x16x32_bf16 v[154:157], v[234:237], v[22:25], v[154:157]
	ds_read_b128 v[234:237], v0 offset:8896
	s_waitcnt lgkmcnt(1)
	v_mfma_f32_16x16x32_bf16 v[146:149], v[194:197], v[18:21], v[146:149]
	ds_read_b128 v[194:197], v0 offset:17344
	s_waitcnt lgkmcnt(1)
	v_mfma_f32_16x16x32_bf16 v[150:153], v[234:237], v[18:21], v[150:153]
	ds_read_b128 v[234:237], v0 offset:25792
	s_waitcnt lgkmcnt(1)
	v_mfma_f32_16x16x32_bf16 v[158:161], v[194:197], v[18:21], v[158:161]
	s_waitcnt lgkmcnt(0)
	v_mfma_f32_16x16x32_bf16 v[154:157], v[234:237], v[18:21], v[154:157]
	s_add_i32 s18, s18, 3
	s_cmpk_eq_i32 s0, 0xa00
	s_cbranch_scc1 .LBB0_1754
	s_bitcmp1_b32 s18, 0
	s_cselect_b32 s2, 0x8400, 0
	s_add_i32 s2, s2, 0
	v_add_u32_e32 v196, s2, v179
	v_add_u32_e32 v0, s2, v225
	v_add_u32_e32 v194, s2, v223
	v_add_u32_e32 v195, s2, v221
	ds_write_b128 v196, v[50:53]
	ds_write_b128 v195, v[58:61]
	ds_write_b128 v194, v[74:77]
	ds_write_b128 v0, v[90:93]
	s_branch .LBB0_1754

.LBB0_1775:
	s_bitcmp1_b32 s8, 0
	s_cselect_b32 s9, 0xc600, 0
	v_add_u32_e32 v246, s9, v245
	ds_read_b128 v[194:197], v246
	ds_read_b128 v[234:237], v246 offset:8448
	s_waitcnt lgkmcnt(1)
	v_mfma_f32_16x16x32_bf16 v[186:189], v[194:197], v[26:29], v[186:189]
	ds_read_b128 v[194:197], v246 offset:16896
	s_waitcnt lgkmcnt(1)
	v_mfma_f32_16x16x32_bf16 v[178:181], v[234:237], v[26:29], v[178:181]
	ds_read_b128 v[234:237], v246 offset:25344
	s_waitcnt lgkmcnt(1)
	v_mfma_f32_16x16x32_bf16 v[170:173], v[194:197], v[26:29], v[170:173]
	ds_read_b128 v[194:197], v246 offset:33792
	s_waitcnt lgkmcnt(1)
	v_mfma_f32_16x16x32_bf16 v[190:193], v[234:237], v[26:29], v[190:193]
	ds_read_b128 v[234:237], v246 offset:42240
	s_waitcnt lgkmcnt(1)
	v_mfma_f32_16x16x32_bf16 v[182:185], v[194:197], v[26:29], v[182:185]
	ds_read_b128 v[194:197], v246 offset:64
	s_waitcnt lgkmcnt(1)
	v_mfma_f32_16x16x32_bf16 v[174:177], v[234:237], v[26:29], v[174:177]
	ds_read_b128 v[234:237], v246 offset:8512
	s_waitcnt lgkmcnt(1)
	v_mfma_f32_16x16x32_bf16 v[186:189], v[194:197], v[38:41], v[186:189]
	ds_read_b128 v[194:197], v246 offset:16960
	s_waitcnt lgkmcnt(1)
	v_mfma_f32_16x16x32_bf16 v[178:181], v[234:237], v[38:41], v[178:181]
	ds_read_b128 v[234:237], v246 offset:25408
	s_waitcnt lgkmcnt(1)
	v_mfma_f32_16x16x32_bf16 v[170:173], v[194:197], v[38:41], v[170:173]
	ds_read_b128 v[194:197], v246 offset:33856
	s_waitcnt lgkmcnt(1)
	v_mfma_f32_16x16x32_bf16 v[190:193], v[234:237], v[38:41], v[190:193]
	ds_read_b128 v[234:237], v246 offset:42304
	s_waitcnt lgkmcnt(1)
	v_mfma_f32_16x16x32_bf16 v[182:185], v[194:197], v[38:41], v[182:185]
	ds_read_b128 v[194:197], v246 offset:128
	s_waitcnt lgkmcnt(1)
	v_mfma_f32_16x16x32_bf16 v[174:177], v[234:237], v[38:41], v[174:177]
	ds_read_b128 v[234:237], v246 offset:8576
	s_waitcnt lgkmcnt(1)
	v_mfma_f32_16x16x32_bf16 v[186:189], v[194:197], v[42:45], v[186:189]
	ds_read_b128 v[194:197], v246 offset:17024
	s_waitcnt lgkmcnt(1)
	v_mfma_f32_16x16x32_bf16 v[178:181], v[234:237], v[42:45], v[178:181]
	ds_read_b128 v[234:237], v246 offset:25472
	s_waitcnt lgkmcnt(1)
	v_mfma_f32_16x16x32_bf16 v[170:173], v[194:197], v[42:45], v[170:173]
	ds_read_b128 v[194:197], v246 offset:33920
	s_waitcnt lgkmcnt(1)
	v_mfma_f32_16x16x32_bf16 v[190:193], v[234:237], v[42:45], v[190:193]
	ds_read_b128 v[234:237], v246 offset:42368
	s_waitcnt lgkmcnt(1)
	v_mfma_f32_16x16x32_bf16 v[182:185], v[194:197], v[42:45], v[182:185]
	ds_read_b128 v[194:197], v246 offset:192
	s_waitcnt lgkmcnt(1)
	v_mfma_f32_16x16x32_bf16 v[174:177], v[234:237], v[42:45], v[174:177]
	ds_read_b128 v[234:237], v246 offset:8640
	s_waitcnt lgkmcnt(1)
	v_mfma_f32_16x16x32_bf16 v[186:189], v[194:197], v[46:49], v[186:189]
	ds_read_b128 v[194:197], v246 offset:17088
	s_waitcnt lgkmcnt(1)
	v_mfma_f32_16x16x32_bf16 v[178:181], v[234:237], v[46:49], v[178:181]
	ds_read_b128 v[234:237], v246 offset:25536
	s_waitcnt lgkmcnt(1)
	v_mfma_f32_16x16x32_bf16 v[170:173], v[194:197], v[46:49], v[170:173]
	ds_read_b128 v[194:197], v246 offset:33984
	s_waitcnt lgkmcnt(1)
	v_mfma_f32_16x16x32_bf16 v[190:193], v[234:237], v[46:49], v[190:193]
	ds_read_b128 v[234:237], v246 offset:42432
	s_waitcnt lgkmcnt(1)
	v_mfma_f32_16x16x32_bf16 v[182:185], v[194:197], v[46:49], v[182:185]
	ds_read_b128 v[194:197], v246 offset:256
	s_waitcnt lgkmcnt(1)
	v_mfma_f32_16x16x32_bf16 v[174:177], v[234:237], v[46:49], v[174:177]
	ds_read_b128 v[234:237], v246 offset:8704
	s_waitcnt lgkmcnt(1)
	v_mfma_f32_16x16x32_bf16 v[186:189], v[194:197], v[58:61], v[186:189]
	ds_read_b128 v[194:197], v246 offset:17152
	s_waitcnt lgkmcnt(1)
	v_mfma_f32_16x16x32_bf16 v[178:181], v[234:237], v[58:61], v[178:181]
	ds_read_b128 v[234:237], v246 offset:25600
	s_waitcnt lgkmcnt(1)
	v_mfma_f32_16x16x32_bf16 v[170:173], v[194:197], v[58:61], v[170:173]
	ds_read_b128 v[194:197], v246 offset:34048
	s_waitcnt lgkmcnt(1)
	v_mfma_f32_16x16x32_bf16 v[190:193], v[234:237], v[58:61], v[190:193]
	ds_read_b128 v[234:237], v246 offset:42496
	s_waitcnt lgkmcnt(1)
	v_mfma_f32_16x16x32_bf16 v[182:185], v[194:197], v[58:61], v[182:185]
	ds_read_b128 v[194:197], v246 offset:320
	s_waitcnt lgkmcnt(1)
	v_mfma_f32_16x16x32_bf16 v[174:177], v[234:237], v[58:61], v[174:177]
	ds_read_b128 v[234:237], v246 offset:8768
	s_waitcnt lgkmcnt(1)
	v_mfma_f32_16x16x32_bf16 v[186:189], v[194:197], v[62:65], v[186:189]
	ds_read_b128 v[194:197], v246 offset:17216
	s_waitcnt lgkmcnt(1)
	v_mfma_f32_16x16x32_bf16 v[178:181], v[234:237], v[62:65], v[178:181]
	ds_read_b128 v[234:237], v246 offset:25664
	s_waitcnt lgkmcnt(1)
	v_mfma_f32_16x16x32_bf16 v[170:173], v[194:197], v[62:65], v[170:173]
	ds_read_b128 v[194:197], v246 offset:34112
	s_waitcnt lgkmcnt(1)
	v_mfma_f32_16x16x32_bf16 v[190:193], v[234:237], v[62:65], v[190:193]
	ds_read_b128 v[234:237], v246 offset:42560
	s_waitcnt lgkmcnt(1)
	v_mfma_f32_16x16x32_bf16 v[182:185], v[194:197], v[62:65], v[182:185]
	ds_read_b128 v[194:197], v246 offset:384
	s_waitcnt lgkmcnt(1)
	v_mfma_f32_16x16x32_bf16 v[174:177], v[234:237], v[62:65], v[174:177]
	ds_read_b128 v[234:237], v246 offset:8832
	s_waitcnt lgkmcnt(1)
	v_mfma_f32_16x16x32_bf16 v[186:189], v[194:197], v[74:77], v[186:189]
	ds_read_b128 v[194:197], v246 offset:17280
	s_waitcnt lgkmcnt(1)
	v_mfma_f32_16x16x32_bf16 v[178:181], v[234:237], v[74:77], v[178:181]
	s_waitcnt lgkmcnt(0)
	v_mfma_f32_16x16x32_bf16 v[194:197], v[194:197], v[74:77], v[170:173]
	s_nop 2
	ds_read_b128 v[170:173], v246 offset:25728
	s_waitcnt lgkmcnt(0)
	v_mfma_f32_16x16x32_bf16 v[190:193], v[170:173], v[74:77], v[190:193]
	ds_read_b128 v[170:173], v246 offset:34176
	s_waitcnt lgkmcnt(0)
	v_mfma_f32_16x16x32_bf16 v[198:201], v[170:173], v[74:77], v[182:185]
	ds_read_b128 v[170:173], v246 offset:42624
	s_nop 1
	ds_read_b128 v[182:185], v246 offset:25792
	s_waitcnt lgkmcnt(1)
	v_mfma_f32_16x16x32_bf16 v[202:205], v[170:173], v[74:77], v[174:177]
	ds_read_b128 v[170:173], v246 offset:448
	s_nop 1
	ds_read_b128 v[174:177], v246 offset:8896
	s_waitcnt lgkmcnt(1)
	v_mfma_f32_16x16x32_bf16 v[170:173], v[170:173], v[78:81], v[186:189]
	s_nop 2
	ds_read_b128 v[186:189], v246 offset:34240
	s_waitcnt lgkmcnt(1)
	v_mfma_f32_16x16x32_bf16 v[174:177], v[174:177], v[78:81], v[178:181]
	s_nop 2
	ds_read_b128 v[178:181], v246 offset:17344
	v_mfma_f32_16x16x32_bf16 v[182:185], v[182:185], v[78:81], v[190:193]
	s_nop 2
	ds_read_b128 v[190:193], v246 offset:42688
	s_waitcnt lgkmcnt(1)
	v_mfma_f32_16x16x32_bf16 v[178:181], v[178:181], v[78:81], v[194:197]
	v_mfma_f32_16x16x32_bf16 v[186:189], v[186:189], v[78:81], v[198:201]
	s_waitcnt lgkmcnt(0)
	v_mfma_f32_16x16x32_bf16 v[190:193], v[190:193], v[78:81], v[202:205]
	s_cselect_b32 s2, 0, 0xc600
	s_add_i32 s3, s2, 0
	v_add_u32_e32 v194, s3, v239
	s_waitcnt vmcnt(13)
	ds_write_b128 v194, v[6:9]
	v_add_u32_e32 v194, s3, v240
	s_waitcnt vmcnt(12)
	ds_write_b128 v194, v[14:17]
	v_add_u32_e32 v194, s3, v241
	s_waitcnt vmcnt(11)
	ds_write_b128 v194, v[22:25]
	v_add_u32_e32 v194, s3, v242
	s_waitcnt vmcnt(10)
	ds_write_b128 v194, v[34:37]
	v_add_u32_e32 v194, s3, v243
	s_waitcnt vmcnt(9)
	ds_write_b128 v194, v[54:57]
	v_add_u32_e32 v194, s3, v244
	s_waitcnt vmcnt(8)
	ds_write_b128 v194, v[70:73]
	s_waitcnt lgkmcnt(0)
	s_barrier
	s_cmp_gt_u32 s8, 4
	s_cbranch_scc1 .LBB0_1777
	v_lshl_add_u64 v[2:3], v[224:225], 0, s[0:1]
	v_lshl_add_u64 v[10:11], v[222:223], 0, s[0:1]
	v_lshl_add_u64 v[18:19], v[220:221], 0, s[0:1]
	v_lshl_add_u64 v[26:27], v[218:219], 0, s[0:1]
	global_load_dwordx4 v[2:5], v[2:3], off
	s_nop 0
	global_load_dwordx4 v[10:13], v[10:11], off
	s_nop 0
	global_load_dwordx4 v[18:21], v[18:19], off
	s_nop 0
	global_load_dwordx4 v[30:33], v[26:27], off
	v_lshl_add_u64 v[26:27], v[216:217], 0, s[0:1]
	v_lshl_add_u64 v[28:29], v[214:215], 0, s[0:1]
	global_load_dwordx4 v[50:53], v[26:27], off
	global_load_dwordx4 v[66:69], v[28:29], off
	v_lshl_add_u64 v[26:27], v[212:213], 0, s[0:1]
	v_add_co_u32_e32 v78, vcc, 0x1ca00000, v26
	s_nop 1
	v_addc_co_u32_e32 v79, vcc, 0, v27, vcc
	global_load_dwordx4 v[26:29], v[78:79], off offset:1536
	global_load_dwordx4 v[38:41], v[78:79], off offset:1600
	global_load_dwordx4 v[42:45], v[78:79], off offset:1664
	global_load_dwordx4 v[46:49], v[78:79], off offset:1728
	global_load_dwordx4 v[58:61], v[78:79], off offset:1792
	global_load_dwordx4 v[62:65], v[78:79], off offset:1856
	global_load_dwordx4 v[74:77], v[78:79], off offset:1920
	s_nop 0
	global_load_dwordx4 v[78:81], v[78:79], off offset:1984
.LBB0_1777:
	v_add_u32_e32 v206, s2, v245
	ds_read_b128 v[194:197], v206
	ds_read_b128 v[234:237], v206 offset:8448
	s_waitcnt vmcnt(7) lgkmcnt(1)
	v_mfma_f32_16x16x32_bf16 v[170:173], v[194:197], v[82:85], v[170:173]
	ds_read_b128 v[194:197], v206 offset:16896
	s_waitcnt lgkmcnt(1)
	v_mfma_f32_16x16x32_bf16 v[174:177], v[234:237], v[82:85], v[174:177]
	ds_read_b128 v[234:237], v206 offset:25344
	s_waitcnt lgkmcnt(1)
	v_mfma_f32_16x16x32_bf16 v[178:181], v[194:197], v[82:85], v[178:181]
	ds_read_b128 v[194:197], v206 offset:33792
	s_waitcnt lgkmcnt(1)
	v_mfma_f32_16x16x32_bf16 v[182:185], v[234:237], v[82:85], v[182:185]
	ds_read_b128 v[234:237], v206 offset:42240
	s_waitcnt lgkmcnt(1)
	v_mfma_f32_16x16x32_bf16 v[186:189], v[194:197], v[82:85], v[186:189]
	ds_read_b128 v[194:197], v206 offset:64
	s_waitcnt lgkmcnt(1)
	v_mfma_f32_16x16x32_bf16 v[190:193], v[234:237], v[82:85], v[190:193]
	ds_read_b128 v[234:237], v206 offset:8512
	s_waitcnt vmcnt(6) lgkmcnt(1)
	v_mfma_f32_16x16x32_bf16 v[170:173], v[194:197], v[86:89], v[170:173]
	ds_read_b128 v[194:197], v206 offset:16960
	s_waitcnt lgkmcnt(1)
	v_mfma_f32_16x16x32_bf16 v[174:177], v[234:237], v[86:89], v[174:177]
	ds_read_b128 v[234:237], v206 offset:25408
	s_waitcnt lgkmcnt(1)
	v_mfma_f32_16x16x32_bf16 v[178:181], v[194:197], v[86:89], v[178:181]
	ds_read_b128 v[194:197], v206 offset:33856
	s_waitcnt lgkmcnt(1)
	v_mfma_f32_16x16x32_bf16 v[182:185], v[234:237], v[86:89], v[182:185]
	ds_read_b128 v[234:237], v206 offset:42304
	s_waitcnt lgkmcnt(1)
	v_mfma_f32_16x16x32_bf16 v[186:189], v[194:197], v[86:89], v[186:189]
	ds_read_b128 v[194:197], v206 offset:128
	s_waitcnt lgkmcnt(1)
	v_mfma_f32_16x16x32_bf16 v[190:193], v[234:237], v[86:89], v[190:193]
	ds_read_b128 v[234:237], v206 offset:8576
	s_waitcnt vmcnt(5) lgkmcnt(1)
	v_mfma_f32_16x16x32_bf16 v[170:173], v[194:197], v[90:93], v[170:173]
	ds_read_b128 v[194:197], v206 offset:17024
	s_waitcnt lgkmcnt(1)
	v_mfma_f32_16x16x32_bf16 v[174:177], v[234:237], v[90:93], v[174:177]
	ds_read_b128 v[234:237], v206 offset:25472
	s_waitcnt lgkmcnt(1)
	v_mfma_f32_16x16x32_bf16 v[178:181], v[194:197], v[90:93], v[178:181]
	ds_read_b128 v[194:197], v206 offset:33920
	s_waitcnt lgkmcnt(1)
	v_mfma_f32_16x16x32_bf16 v[182:185], v[234:237], v[90:93], v[182:185]
	ds_read_b128 v[234:237], v206 offset:42368
	s_waitcnt lgkmcnt(1)
	v_mfma_f32_16x16x32_bf16 v[186:189], v[194:197], v[90:93], v[186:189]
	ds_read_b128 v[194:197], v206 offset:192
	s_waitcnt lgkmcnt(1)
	v_mfma_f32_16x16x32_bf16 v[190:193], v[234:237], v[90:93], v[190:193]
	ds_read_b128 v[234:237], v206 offset:8640
	s_waitcnt vmcnt(4) lgkmcnt(1)
	v_mfma_f32_16x16x32_bf16 v[170:173], v[194:197], v[94:97], v[170:173]
	ds_read_b128 v[194:197], v206 offset:17088
	s_waitcnt lgkmcnt(1)
	v_mfma_f32_16x16x32_bf16 v[174:177], v[234:237], v[94:97], v[174:177]
	ds_read_b128 v[234:237], v206 offset:25536
	s_waitcnt lgkmcnt(1)
	v_mfma_f32_16x16x32_bf16 v[178:181], v[194:197], v[94:97], v[178:181]
	ds_read_b128 v[194:197], v206 offset:33984
	s_waitcnt lgkmcnt(1)
	v_mfma_f32_16x16x32_bf16 v[182:185], v[234:237], v[94:97], v[182:185]
	ds_read_b128 v[234:237], v206 offset:42432
	s_waitcnt lgkmcnt(1)
	v_mfma_f32_16x16x32_bf16 v[186:189], v[194:197], v[94:97], v[186:189]
	ds_read_b128 v[194:197], v206 offset:256
	s_waitcnt lgkmcnt(1)
	v_mfma_f32_16x16x32_bf16 v[190:193], v[234:237], v[94:97], v[190:193]
	ds_read_b128 v[234:237], v206 offset:8704
	s_waitcnt vmcnt(3) lgkmcnt(1)
	v_mfma_f32_16x16x32_bf16 v[170:173], v[194:197], v[98:101], v[170:173]
	ds_read_b128 v[194:197], v206 offset:17152
	s_waitcnt lgkmcnt(1)
	v_mfma_f32_16x16x32_bf16 v[174:177], v[234:237], v[98:101], v[174:177]
	ds_read_b128 v[234:237], v206 offset:25600
	s_waitcnt lgkmcnt(1)
	v_mfma_f32_16x16x32_bf16 v[178:181], v[194:197], v[98:101], v[178:181]
	ds_read_b128 v[194:197], v206 offset:34048
	s_waitcnt lgkmcnt(1)
	v_mfma_f32_16x16x32_bf16 v[182:185], v[234:237], v[98:101], v[182:185]
	ds_read_b128 v[234:237], v206 offset:42496
	s_waitcnt lgkmcnt(1)
	v_mfma_f32_16x16x32_bf16 v[186:189], v[194:197], v[98:101], v[186:189]
	ds_read_b128 v[194:197], v206 offset:320
	s_waitcnt lgkmcnt(1)
	v_mfma_f32_16x16x32_bf16 v[190:193], v[234:237], v[98:101], v[190:193]
	ds_read_b128 v[234:237], v206 offset:8768
	s_waitcnt vmcnt(2) lgkmcnt(1)
	v_mfma_f32_16x16x32_bf16 v[170:173], v[194:197], v[102:105], v[170:173]
	ds_read_b128 v[194:197], v206 offset:17216
	s_waitcnt lgkmcnt(1)
	v_mfma_f32_16x16x32_bf16 v[174:177], v[234:237], v[102:105], v[174:177]
	ds_read_b128 v[234:237], v206 offset:25664
	s_waitcnt lgkmcnt(1)
	v_mfma_f32_16x16x32_bf16 v[178:181], v[194:197], v[102:105], v[178:181]
	ds_read_b128 v[194:197], v206 offset:34112
	s_waitcnt lgkmcnt(1)
	v_mfma_f32_16x16x32_bf16 v[182:185], v[234:237], v[102:105], v[182:185]
	ds_read_b128 v[234:237], v206 offset:42560
	s_waitcnt lgkmcnt(1)
	v_mfma_f32_16x16x32_bf16 v[186:189], v[194:197], v[102:105], v[186:189]
	ds_read_b128 v[194:197], v206 offset:384
	s_waitcnt lgkmcnt(1)
	v_mfma_f32_16x16x32_bf16 v[190:193], v[234:237], v[102:105], v[190:193]
	ds_read_b128 v[234:237], v206 offset:8832
	s_waitcnt vmcnt(1) lgkmcnt(1)
	v_mfma_f32_16x16x32_bf16 v[170:173], v[194:197], v[106:109], v[170:173]
	ds_read_b128 v[194:197], v206 offset:17280
	s_waitcnt lgkmcnt(1)
	v_mfma_f32_16x16x32_bf16 v[174:177], v[234:237], v[106:109], v[174:177]
	s_waitcnt lgkmcnt(0)
	v_mfma_f32_16x16x32_bf16 v[194:197], v[194:197], v[106:109], v[178:181]
	s_nop 2
	ds_read_b128 v[178:181], v206 offset:25728
	ds_read_b128 v[234:237], v206 offset:34176
	s_waitcnt lgkmcnt(1)
	v_mfma_f32_16x16x32_bf16 v[182:185], v[178:181], v[106:109], v[182:185]
	ds_read_b128 v[178:181], v206 offset:42624
	s_waitcnt lgkmcnt(1)
	v_mfma_f32_16x16x32_bf16 v[198:201], v[234:237], v[106:109], v[186:189]
	ds_read_b128 v[234:237], v206 offset:448
	s_waitcnt lgkmcnt(1)
	v_mfma_f32_16x16x32_bf16 v[202:205], v[178:181], v[106:109], v[190:193]
	s_waitcnt vmcnt(0) lgkmcnt(0)
	v_mfma_f32_16x16x32_bf16 v[186:189], v[234:237], v[110:113], v[170:173]
	s_nop 2
	ds_read_b128 v[170:173], v206 offset:8896
	s_waitcnt lgkmcnt(0)
	v_mfma_f32_16x16x32_bf16 v[178:181], v[170:173], v[110:113], v[174:177]
	s_nop 2
	ds_read_b128 v[174:177], v206 offset:25792
	ds_read_b128 v[170:173], v206 offset:17344
	s_waitcnt lgkmcnt(1)
	v_mfma_f32_16x16x32_bf16 v[190:193], v[174:177], v[110:113], v[182:185]
	ds_read_b128 v[174:177], v206 offset:34240
	s_waitcnt lgkmcnt(0)
	v_mfma_f32_16x16x32_bf16 v[182:185], v[174:177], v[110:113], v[198:201]
	ds_read_b128 v[174:177], v206 offset:42688
	v_mfma_f32_16x16x32_bf16 v[170:173], v[170:173], v[110:113], v[194:197]
	s_waitcnt lgkmcnt(0)
	v_mfma_f32_16x16x32_bf16 v[174:177], v[174:177], v[110:113], v[202:205]
	s_andn2_b64 vcc, exec, s[6:7]
	s_cbranch_vccnz .LBB0_1779
	s_add_i32 s2, s9, 0
	v_add_u32_e32 v194, s2, v239
	ds_write_b128 v194, v[150:153]
	v_add_u32_e32 v194, s2, v240
	ds_write_b128 v194, v[146:149]
	v_add_u32_e32 v194, s2, v241
	ds_write_b128 v194, v[158:161]
	v_add_u32_e32 v194, s2, v242
	ds_write_b128 v194, v[154:157]
	v_add_u32_e32 v194, s2, v243
	ds_write_b128 v194, v[166:169]
	v_add_u32_e32 v194, s2, v244
	ds_write_b128 v194, v[162:165]

.LBB0_1784:
	ds_read_b128 v[194:197], v246
	ds_read_b128 v[234:237], v246 offset:8448
	s_waitcnt lgkmcnt(1)
	v_mfma_f32_16x16x32_bf16 v[186:189], v[194:197], v[142:145], v[186:189]
	ds_read_b128 v[194:197], v246 offset:16896
	s_waitcnt lgkmcnt(1)
	v_mfma_f32_16x16x32_bf16 v[178:181], v[234:237], v[142:145], v[178:181]
	ds_read_b128 v[234:237], v246 offset:25344
	s_waitcnt lgkmcnt(1)
	v_mfma_f32_16x16x32_bf16 v[170:173], v[194:197], v[142:145], v[170:173]
	ds_read_b128 v[194:197], v246 offset:33792
	s_waitcnt lgkmcnt(1)
	v_mfma_f32_16x16x32_bf16 v[190:193], v[234:237], v[142:145], v[190:193]
	ds_read_b128 v[234:237], v246 offset:42240
	s_waitcnt lgkmcnt(1)
	v_mfma_f32_16x16x32_bf16 v[182:185], v[194:197], v[142:145], v[182:185]
	ds_read_b128 v[194:197], v246 offset:64
	s_waitcnt lgkmcnt(1)
	v_mfma_f32_16x16x32_bf16 v[174:177], v[234:237], v[142:145], v[174:177]
	ds_read_b128 v[234:237], v246 offset:8512
	s_waitcnt lgkmcnt(1)
	v_mfma_f32_16x16x32_bf16 v[186:189], v[194:197], v[138:141], v[186:189]
	ds_read_b128 v[194:197], v246 offset:16960
	s_waitcnt lgkmcnt(1)
	v_mfma_f32_16x16x32_bf16 v[178:181], v[234:237], v[138:141], v[178:181]
	ds_read_b128 v[234:237], v246 offset:25408
	s_waitcnt lgkmcnt(1)
	v_mfma_f32_16x16x32_bf16 v[170:173], v[194:197], v[138:141], v[170:173]
	ds_read_b128 v[194:197], v246 offset:33856
	s_waitcnt lgkmcnt(1)
	v_mfma_f32_16x16x32_bf16 v[190:193], v[234:237], v[138:141], v[190:193]
	ds_read_b128 v[234:237], v246 offset:42304
	s_waitcnt lgkmcnt(1)
	v_mfma_f32_16x16x32_bf16 v[182:185], v[194:197], v[138:141], v[182:185]
	ds_read_b128 v[194:197], v246 offset:128
	s_waitcnt lgkmcnt(1)
	v_mfma_f32_16x16x32_bf16 v[174:177], v[234:237], v[138:141], v[174:177]
	ds_read_b128 v[234:237], v246 offset:8576
	s_waitcnt lgkmcnt(1)
	v_mfma_f32_16x16x32_bf16 v[186:189], v[194:197], v[134:137], v[186:189]
	ds_read_b128 v[194:197], v246 offset:17024
	s_waitcnt lgkmcnt(1)
	v_mfma_f32_16x16x32_bf16 v[178:181], v[234:237], v[134:137], v[178:181]
	ds_read_b128 v[234:237], v246 offset:25472
	s_waitcnt lgkmcnt(1)
	v_mfma_f32_16x16x32_bf16 v[170:173], v[194:197], v[134:137], v[170:173]
	ds_read_b128 v[194:197], v246 offset:33920
	s_waitcnt lgkmcnt(1)
	v_mfma_f32_16x16x32_bf16 v[190:193], v[234:237], v[134:137], v[190:193]
	ds_read_b128 v[234:237], v246 offset:42368
	s_waitcnt lgkmcnt(1)
	v_mfma_f32_16x16x32_bf16 v[182:185], v[194:197], v[134:137], v[182:185]
	ds_read_b128 v[194:197], v246 offset:192
	s_waitcnt lgkmcnt(1)
	v_mfma_f32_16x16x32_bf16 v[174:177], v[234:237], v[134:137], v[174:177]
	ds_read_b128 v[234:237], v246 offset:8640
	s_waitcnt lgkmcnt(1)
	v_mfma_f32_16x16x32_bf16 v[186:189], v[194:197], v[130:133], v[186:189]
	ds_read_b128 v[194:197], v246 offset:17088
	s_waitcnt lgkmcnt(1)
	v_mfma_f32_16x16x32_bf16 v[178:181], v[234:237], v[130:133], v[178:181]
	ds_read_b128 v[234:237], v246 offset:25536
	s_waitcnt lgkmcnt(1)
	v_mfma_f32_16x16x32_bf16 v[170:173], v[194:197], v[130:133], v[170:173]
	ds_read_b128 v[194:197], v246 offset:33984
	s_waitcnt lgkmcnt(1)
	v_mfma_f32_16x16x32_bf16 v[190:193], v[234:237], v[130:133], v[190:193]
	ds_read_b128 v[234:237], v246 offset:42432
	s_waitcnt lgkmcnt(1)
	v_mfma_f32_16x16x32_bf16 v[182:185], v[194:197], v[130:133], v[182:185]
	ds_read_b128 v[194:197], v246 offset:256
	s_waitcnt lgkmcnt(1)
	v_mfma_f32_16x16x32_bf16 v[174:177], v[234:237], v[130:133], v[174:177]
	ds_read_b128 v[234:237], v246 offset:8704
	s_waitcnt lgkmcnt(1)
	v_mfma_f32_16x16x32_bf16 v[186:189], v[194:197], v[126:129], v[186:189]
	ds_read_b128 v[194:197], v246 offset:17152
	s_waitcnt lgkmcnt(1)
	v_mfma_f32_16x16x32_bf16 v[178:181], v[234:237], v[126:129], v[178:181]
	ds_read_b128 v[234:237], v246 offset:25600
	s_waitcnt lgkmcnt(1)
	v_mfma_f32_16x16x32_bf16 v[170:173], v[194:197], v[126:129], v[170:173]
	ds_read_b128 v[194:197], v246 offset:34048
	s_waitcnt lgkmcnt(1)
	v_mfma_f32_16x16x32_bf16 v[190:193], v[234:237], v[126:129], v[190:193]
	ds_read_b128 v[234:237], v246 offset:42496
	s_waitcnt lgkmcnt(1)
	v_mfma_f32_16x16x32_bf16 v[182:185], v[194:197], v[126:129], v[182:185]
	ds_read_b128 v[194:197], v246 offset:320
	s_waitcnt lgkmcnt(1)
	v_mfma_f32_16x16x32_bf16 v[174:177], v[234:237], v[126:129], v[174:177]
	ds_read_b128 v[234:237], v246 offset:8768
	s_waitcnt lgkmcnt(1)
	v_mfma_f32_16x16x32_bf16 v[186:189], v[194:197], v[122:125], v[186:189]
	ds_read_b128 v[194:197], v246 offset:17216
	s_waitcnt lgkmcnt(1)
	v_mfma_f32_16x16x32_bf16 v[178:181], v[234:237], v[122:125], v[178:181]
	ds_read_b128 v[234:237], v246 offset:25664
	s_waitcnt lgkmcnt(1)
	v_mfma_f32_16x16x32_bf16 v[170:173], v[194:197], v[122:125], v[170:173]
	ds_read_b128 v[194:197], v246 offset:34112
	s_waitcnt lgkmcnt(1)
	v_mfma_f32_16x16x32_bf16 v[190:193], v[234:237], v[122:125], v[190:193]
	ds_read_b128 v[234:237], v246 offset:42560
	s_waitcnt lgkmcnt(1)
	v_mfma_f32_16x16x32_bf16 v[182:185], v[194:197], v[122:125], v[182:185]
	ds_read_b128 v[194:197], v246 offset:384
	s_waitcnt lgkmcnt(1)
	v_mfma_f32_16x16x32_bf16 v[174:177], v[234:237], v[122:125], v[174:177]
	ds_read_b128 v[234:237], v246 offset:8832
	s_waitcnt lgkmcnt(1)
	v_mfma_f32_16x16x32_bf16 v[186:189], v[194:197], v[118:121], v[186:189]
	ds_read_b128 v[194:197], v246 offset:17280
	s_waitcnt lgkmcnt(1)
	v_mfma_f32_16x16x32_bf16 v[178:181], v[234:237], v[118:121], v[178:181]
	ds_read_b128 v[234:237], v246 offset:25728
	s_waitcnt lgkmcnt(1)
	v_mfma_f32_16x16x32_bf16 v[170:173], v[194:197], v[118:121], v[170:173]
	ds_read_b128 v[194:197], v246 offset:34176
	s_waitcnt lgkmcnt(1)
	v_mfma_f32_16x16x32_bf16 v[190:193], v[234:237], v[118:121], v[190:193]
	ds_read_b128 v[234:237], v246 offset:42624
	s_waitcnt lgkmcnt(1)
	v_mfma_f32_16x16x32_bf16 v[182:185], v[194:197], v[118:121], v[182:185]
	ds_read_b128 v[194:197], v246 offset:448
	s_waitcnt lgkmcnt(1)
	v_mfma_f32_16x16x32_bf16 v[174:177], v[234:237], v[118:121], v[174:177]
	ds_read_b128 v[234:237], v246 offset:8896
	s_waitcnt lgkmcnt(1)
	v_mfma_f32_16x16x32_bf16 v[186:189], v[194:197], v[114:117], v[186:189]
	ds_read_b128 v[194:197], v246 offset:17344
	s_waitcnt lgkmcnt(1)
	v_mfma_f32_16x16x32_bf16 v[178:181], v[234:237], v[114:117], v[178:181]
	ds_read_b128 v[234:237], v246 offset:25792
	s_waitcnt lgkmcnt(1)
	v_mfma_f32_16x16x32_bf16 v[170:173], v[194:197], v[114:117], v[170:173]
	ds_read_b128 v[194:197], v246 offset:34240
	s_waitcnt lgkmcnt(1)
	v_mfma_f32_16x16x32_bf16 v[190:193], v[234:237], v[114:117], v[190:193]
	ds_read_b128 v[234:237], v246 offset:42688
	s_waitcnt lgkmcnt(1)
	v_mfma_f32_16x16x32_bf16 v[182:185], v[194:197], v[114:117], v[182:185]
	s_waitcnt lgkmcnt(0)
	v_mfma_f32_16x16x32_bf16 v[174:177], v[234:237], v[114:117], v[174:177]
	s_add_i32 s8, s8, 3
	s_cmpk_eq_i32 s0, 0xa00
	s_cbranch_scc1 .LBB0_1772
	s_bitcmp1_b32 s8, 0
	s_cselect_b32 s2, 0xc600, 0
	s_add_i32 s2, s2, 0
	v_add_u32_e32 v194, s2, v239
	ds_write_b128 v194, v[2:5]
	v_add_u32_e32 v194, s2, v240
	ds_write_b128 v194, v[10:13]
	v_add_u32_e32 v194, s2, v241
	ds_write_b128 v194, v[18:21]
	v_add_u32_e32 v194, s2, v242
	ds_write_b128 v194, v[30:33]
	v_add_u32_e32 v194, s2, v243
	ds_write_b128 v194, v[50:53]
	v_add_u32_e32 v194, s2, v244
	ds_write_b128 v194, v[66:69]
	s_branch .LBB0_1772

.LBB0_1963:
	s_cmp_lt_u32 s2, 9
	s_cselect_b64 s[10:11], -1, 0
	s_cmp_gt_u32 s2, 8
	s_cselect_b64 s[8:9], -1, 0
	s_and_b64 vcc, exec, s[8:9]
	s_cbranch_vccnz .Lti_s1skip
	v_lshl_add_u64 v[2:3], v[178:179], 0, s[4:5]
	v_lshl_add_u64 v[4:5], v[180:181], 0, s[4:5]
	v_lshl_add_u64 v[10:11], v[182:183], 0, s[4:5]
	v_lshl_add_u64 v[12:13], v[184:185], 0, s[4:5]
	v_lshl_add_u64 v[18:19], v[176:177], 0, s[4:5]
	global_load_dwordx4 v[6:9], v[2:3], off offset:-1024
	s_nop 0
	global_load_dwordx4 v[2:5], v[4:5], off offset:-1024
	s_nop 0
	global_load_dwordx4 v[14:17], v[10:11], off offset:-1024
	s_nop 0
	global_load_dwordx4 v[10:13], v[12:13], off offset:-1024
	s_nop 0
	global_load_dwordx4 v[46:49], v[18:19], off offset:-768
	global_load_dwordx4 v[42:45], v[18:19], off offset:-704
	global_load_dwordx4 v[38:41], v[18:19], off offset:-640
	global_load_dwordx4 v[34:37], v[18:19], off offset:-576
	global_load_dwordx4 v[30:33], v[18:19], off offset:-512
	global_load_dwordx4 v[26:29], v[18:19], off offset:-448
	global_load_dwordx4 v[22:25], v[18:19], off offset:-384
	s_nop 0
	global_load_dwordx4 v[18:21], v[18:19], off offset:-320
	s_waitcnt vmcnt(24)
	s_branch .LBB0_1965
.Lti_s1skip:
	s_waitcnt vmcnt(12)
.LBB0_1965:
	s_bitcmp1_b32 s2, 0
	s_cselect_b32 s3, 0x8400, 0
	v_add_u32_e32 v213, s3, v212
	ds_read_b128 v[194:197], v213
	ds_read_b128 v[200:203], v213 offset:8448
	ds_read_b128 v[204:207], v213 offset:64
	ds_read_b128 v[214:217], v213 offset:8512
	ds_read_b128 v[218:221], v213 offset:128
	ds_read_b128 v[234:237], v213 offset:8576
	ds_read_b128 v[238:241], v213 offset:192
	ds_read_b128 v[242:245], v213 offset:8640
	ds_read_b128 v[246:249], v213 offset:256
	s_waitcnt lgkmcnt(8)
	v_mfma_f32_16x16x32_bf16 v[146:149], v[194:197], v[50:53], v[146:149]
	ds_read_b128 v[194:197], v213 offset:8704
	s_waitcnt lgkmcnt(8)
	v_mfma_f32_16x16x32_bf16 v[150:153], v[200:203], v[50:53], v[150:153]
	ds_read_b128 v[200:203], v213 offset:320
	s_waitcnt lgkmcnt(8)
	v_mfma_f32_16x16x32_bf16 v[146:149], v[204:207], v[62:65], v[146:149]
	ds_read_b128 v[204:207], v213 offset:8768
	s_waitcnt lgkmcnt(8)
	v_mfma_f32_16x16x32_bf16 v[150:153], v[214:217], v[62:65], v[150:153]
	ds_read_b128 v[214:217], v213 offset:384
	s_waitcnt lgkmcnt(8)
	v_mfma_f32_16x16x32_bf16 v[146:149], v[218:221], v[74:77], v[146:149]
	ds_read_b128 v[218:221], v213 offset:8832
	s_waitcnt lgkmcnt(8)
	v_mfma_f32_16x16x32_bf16 v[150:153], v[234:237], v[74:77], v[150:153]
	ds_read_b128 v[234:237], v213 offset:448
	s_waitcnt lgkmcnt(8)
	v_mfma_f32_16x16x32_bf16 v[146:149], v[238:241], v[78:81], v[146:149]
	ds_read_b128 v[238:241], v213 offset:8896
	s_waitcnt lgkmcnt(8)
	v_mfma_f32_16x16x32_bf16 v[150:153], v[242:245], v[78:81], v[150:153]
	s_waitcnt lgkmcnt(7)
	v_mfma_f32_16x16x32_bf16 v[146:149], v[246:249], v[82:85], v[146:149]
	s_waitcnt lgkmcnt(6)
	v_mfma_f32_16x16x32_bf16 v[150:153], v[194:197], v[82:85], v[150:153]
	s_waitcnt lgkmcnt(5)
	v_mfma_f32_16x16x32_bf16 v[146:149], v[200:203], v[94:97], v[146:149]
	s_waitcnt lgkmcnt(4)
	v_mfma_f32_16x16x32_bf16 v[150:153], v[204:207], v[94:97], v[150:153]
	s_waitcnt lgkmcnt(3)
	v_mfma_f32_16x16x32_bf16 v[146:149], v[214:217], v[98:101], v[146:149]
	s_waitcnt lgkmcnt(2)
	v_mfma_f32_16x16x32_bf16 v[150:153], v[218:221], v[98:101], v[150:153]
	s_waitcnt lgkmcnt(1)
	v_mfma_f32_16x16x32_bf16 v[146:149], v[234:237], v[110:113], v[146:149]
	s_waitcnt lgkmcnt(0)
	v_mfma_f32_16x16x32_bf16 v[150:153], v[238:241], v[110:113], v[150:153]
	s_cselect_b32 s16, 0, 0x8400
	s_add_i32 s17, s16, 0
	v_add_u32_e32 v197, s17, v187
	v_add_u32_e32 v194, s17, v190
	v_add_u32_e32 v195, s17, v189
	v_add_u32_e32 v196, s17, v188
	s_cmp_lg_u64 s[8:9], 0
	s_cbranch_scc1 .Lti_w1orig
	s_waitcnt vmcnt(20)
	ds_write_b128 v197, v[58:61]
	ds_write_b128 v196, v[70:73]
	ds_write_b128 v195, v[90:93]
	ds_write_b128 v194, v[106:109]
	s_branch .Lti_w1join
.Lti_w1orig:
	s_waitcnt vmcnt(11)
	ds_write_b128 v197, v[58:61]
	s_waitcnt vmcnt(10)
	ds_write_b128 v196, v[70:73]
	s_waitcnt vmcnt(9)
	ds_write_b128 v195, v[90:93]
	s_waitcnt vmcnt(8)
	ds_write_b128 v194, v[106:109]
.Lti_w1join:
	s_waitcnt lgkmcnt(0)
	s_barrier
	s_cmp_gt_u32 s2, 7
	s_cbranch_scc1 .LBB0_1967
	v_lshl_add_u64 v[50:51], v[178:179], 0, s[4:5]
	v_lshl_add_u64 v[52:53], v[180:181], 0, s[4:5]
	global_load_dwordx4 v[54:57], v[50:51], off offset:-512
	global_load_dwordx4 v[66:69], v[52:53], off offset:-512
	v_lshl_add_u64 v[50:51], v[182:183], 0, s[4:5]
	v_lshl_add_u64 v[52:53], v[184:185], 0, s[4:5]
	v_lshl_add_u64 v[110:111], v[176:177], 0, s[4:5]
	global_load_dwordx4 v[86:89], v[50:51], off offset:-512
	global_load_dwordx4 v[102:105], v[52:53], off offset:-512
	s_nop 0
	global_load_dwordx4 v[50:53], v[110:111], off offset:-256
	global_load_dwordx4 v[62:65], v[110:111], off offset:-192
	global_load_dwordx4 v[74:77], v[110:111], off offset:-128
	global_load_dwordx4 v[78:81], v[110:111], off offset:-64
	global_load_dwordx4 v[82:85], v[110:111], off
	global_load_dwordx4 v[94:97], v[110:111], off offset:64
	global_load_dwordx4 v[98:101], v[110:111], off offset:128
	s_nop 0
	global_load_dwordx4 v[110:113], v[110:111], off offset:192
.LBB0_1967:
	s_cbranch_scc1 .Lti_s2slow
	s_waitcnt vmcnt(24)
	s_branch .Lti_s2go

.Lti_s2go:
	v_add_u32_e32 v198, s16, v212
	ds_read_b128 v[194:197], v198
	ds_read_b128 v[200:203], v198 offset:8448
	ds_read_b128 v[204:207], v198 offset:64
	ds_read_b128 v[214:217], v198 offset:8512
	ds_read_b128 v[218:221], v198 offset:128
	ds_read_b128 v[234:237], v198 offset:8576
	ds_read_b128 v[238:241], v198 offset:192
	ds_read_b128 v[242:245], v198 offset:8640
	ds_read_b128 v[246:249], v198 offset:256
	s_waitcnt lgkmcnt(8)
	v_mfma_f32_16x16x32_bf16 v[146:149], v[194:197], v[114:117], v[146:149]
	ds_read_b128 v[194:197], v198 offset:8704
	s_waitcnt lgkmcnt(8)
	v_mfma_f32_16x16x32_bf16 v[150:153], v[200:203], v[114:117], v[150:153]
	ds_read_b128 v[200:203], v198 offset:320
	s_waitcnt lgkmcnt(8)
	v_mfma_f32_16x16x32_bf16 v[146:149], v[204:207], v[118:121], v[146:149]
	ds_read_b128 v[204:207], v198 offset:8768
	s_waitcnt lgkmcnt(8)
	v_mfma_f32_16x16x32_bf16 v[150:153], v[214:217], v[118:121], v[150:153]
	ds_read_b128 v[214:217], v198 offset:384
	s_waitcnt lgkmcnt(8)
	v_mfma_f32_16x16x32_bf16 v[146:149], v[218:221], v[122:125], v[146:149]
	ds_read_b128 v[218:221], v198 offset:8832
	s_waitcnt lgkmcnt(8)
	v_mfma_f32_16x16x32_bf16 v[150:153], v[234:237], v[122:125], v[150:153]
	ds_read_b128 v[234:237], v198 offset:448
	s_waitcnt lgkmcnt(8)
	v_mfma_f32_16x16x32_bf16 v[146:149], v[238:241], v[126:129], v[146:149]
	ds_read_b128 v[238:241], v198 offset:8896
	s_waitcnt lgkmcnt(8)
	v_mfma_f32_16x16x32_bf16 v[150:153], v[242:245], v[126:129], v[150:153]
	s_waitcnt lgkmcnt(7)
	v_mfma_f32_16x16x32_bf16 v[146:149], v[246:249], v[130:133], v[146:149]
	s_waitcnt lgkmcnt(6)
	v_mfma_f32_16x16x32_bf16 v[150:153], v[194:197], v[130:133], v[150:153]
	s_waitcnt lgkmcnt(5)
	v_mfma_f32_16x16x32_bf16 v[146:149], v[200:203], v[134:137], v[146:149]
	s_waitcnt lgkmcnt(4)
	v_mfma_f32_16x16x32_bf16 v[150:153], v[204:207], v[134:137], v[150:153]
	s_waitcnt lgkmcnt(3)
	v_mfma_f32_16x16x32_bf16 v[146:149], v[214:217], v[138:141], v[146:149]
	s_waitcnt lgkmcnt(2)
	v_mfma_f32_16x16x32_bf16 v[150:153], v[218:221], v[138:141], v[150:153]
	s_waitcnt lgkmcnt(1)
	v_mfma_f32_16x16x32_bf16 v[146:149], v[234:237], v[142:145], v[146:149]
	s_waitcnt lgkmcnt(0)
	v_mfma_f32_16x16x32_bf16 v[150:153], v[238:241], v[142:145], v[150:153]
	s_andn2_b64 vcc, exec, s[10:11]
	s_cbranch_vccnz .LBB0_1969
	s_add_i32 s3, s3, 0
	v_add_u32_e32 v197, s3, v187
	v_add_u32_e32 v194, s3, v190
	v_add_u32_e32 v195, s3, v189
	v_add_u32_e32 v196, s3, v188
	s_waitcnt vmcnt(20)
	ds_write_b128 v197, v[6:9]
	ds_write_b128 v196, v[2:5]
	ds_write_b128 v195, v[14:17]
	ds_write_b128 v194, v[10:13]

.LBB0_1971:
	s_andn2_b64 vcc, exec, s[8:9]
	s_cbranch_vccnz .LBB0_1976
	s_cmp_gt_u32 s2, 6
	s_cbranch_scc1 .Lti_s3skip
	v_lshl_add_u64 v[58:59], v[178:179], 0, s[4:5]
	v_lshl_add_u64 v[70:71], v[180:181], 0, s[4:5]
	v_lshl_add_u64 v[90:91], v[182:183], 0, s[4:5]
	v_lshl_add_u64 v[106:107], v[184:185], 0, s[4:5]
	v_lshl_add_u64 v[142:143], v[176:177], 0, s[4:5]
	global_load_dwordx4 v[58:61], v[58:59], off
	s_nop 0
	global_load_dwordx4 v[70:73], v[70:71], off
	s_nop 0
	global_load_dwordx4 v[90:93], v[90:91], off
	s_nop 0
	global_load_dwordx4 v[106:109], v[106:107], off
	s_nop 0
	global_load_dwordx4 v[114:117], v[142:143], off offset:256
	global_load_dwordx4 v[118:121], v[142:143], off offset:320
	global_load_dwordx4 v[122:125], v[142:143], off offset:384
	global_load_dwordx4 v[126:129], v[142:143], off offset:448
	global_load_dwordx4 v[130:133], v[142:143], off offset:512
	global_load_dwordx4 v[134:137], v[142:143], off offset:576
	global_load_dwordx4 v[138:141], v[142:143], off offset:640
	s_nop 0
	global_load_dwordx4 v[142:145], v[142:143], off offset:704
	s_waitcnt vmcnt(24)
	s_mov_b32 s100, 20
	s_branch .LBB0_1974
.Lti_s3skip:
	s_waitcnt vmcnt(12)
	s_mov_b32 s100, 8
.LBB0_1974:
	ds_read_b128 v[194:197], v213
	ds_read_b128 v[200:203], v213 offset:8448
	ds_read_b128 v[204:207], v213 offset:64
	ds_read_b128 v[214:217], v213 offset:8512
	ds_read_b128 v[218:221], v213 offset:128
	ds_read_b128 v[234:237], v213 offset:8576
	ds_read_b128 v[238:241], v213 offset:192
	ds_read_b128 v[242:245], v213 offset:8640
	ds_read_b128 v[246:249], v213 offset:256
	s_waitcnt lgkmcnt(8)
	v_mfma_f32_16x16x32_bf16 v[146:149], v[194:197], v[46:49], v[146:149]
	ds_read_b128 v[194:197], v213 offset:8704
	s_waitcnt lgkmcnt(8)
	v_mfma_f32_16x16x32_bf16 v[150:153], v[200:203], v[46:49], v[150:153]
	ds_read_b128 v[200:203], v213 offset:320
	s_waitcnt lgkmcnt(8)
	v_mfma_f32_16x16x32_bf16 v[146:149], v[204:207], v[42:45], v[146:149]
	ds_read_b128 v[204:207], v213 offset:8768
	s_waitcnt lgkmcnt(8)
	v_mfma_f32_16x16x32_bf16 v[150:153], v[214:217], v[42:45], v[150:153]
	ds_read_b128 v[214:217], v213 offset:384
	s_waitcnt lgkmcnt(8)
	v_mfma_f32_16x16x32_bf16 v[146:149], v[218:221], v[38:41], v[146:149]
	ds_read_b128 v[218:221], v213 offset:8832
	s_waitcnt lgkmcnt(8)
	v_mfma_f32_16x16x32_bf16 v[150:153], v[234:237], v[38:41], v[150:153]
	ds_read_b128 v[234:237], v213 offset:448
	s_waitcnt lgkmcnt(8)
	v_mfma_f32_16x16x32_bf16 v[146:149], v[238:241], v[34:37], v[146:149]
	ds_read_b128 v[238:241], v213 offset:8896
	s_waitcnt lgkmcnt(8)
	v_mfma_f32_16x16x32_bf16 v[150:153], v[242:245], v[34:37], v[150:153]
	s_waitcnt lgkmcnt(7)
	v_mfma_f32_16x16x32_bf16 v[146:149], v[246:249], v[30:33], v[146:149]
	s_waitcnt lgkmcnt(6)
	v_mfma_f32_16x16x32_bf16 v[150:153], v[194:197], v[30:33], v[150:153]
	s_waitcnt lgkmcnt(5)
	v_mfma_f32_16x16x32_bf16 v[146:149], v[200:203], v[26:29], v[146:149]
	s_waitcnt lgkmcnt(4)
	v_mfma_f32_16x16x32_bf16 v[150:153], v[204:207], v[26:29], v[150:153]
	s_waitcnt lgkmcnt(3)
	v_mfma_f32_16x16x32_bf16 v[146:149], v[214:217], v[22:25], v[146:149]
	s_waitcnt lgkmcnt(2)
	v_mfma_f32_16x16x32_bf16 v[150:153], v[218:221], v[22:25], v[150:153]
	s_waitcnt lgkmcnt(1)
	v_mfma_f32_16x16x32_bf16 v[146:149], v[234:237], v[18:21], v[146:149]
	s_waitcnt lgkmcnt(0)
	v_mfma_f32_16x16x32_bf16 v[150:153], v[238:241], v[18:21], v[150:153]
	s_add_i32 s2, s2, 3
	s_cmpk_eq_i32 s4, 0x1000
	s_cbranch_scc1 .LBB0_1962
	s_bitcmp1_b32 s2, 0
	s_cselect_b32 s3, 0x8400, 0
	s_add_i32 s3, s3, 0
	v_add_u32_e32 v197, s3, v187
	v_add_u32_e32 v194, s3, v190
	v_add_u32_e32 v195, s3, v189
	v_add_u32_e32 v196, s3, v188
	s_cmp_eq_u32 s100, 20
	s_cbranch_scc1 .Lti_w3f
	s_waitcnt vmcnt(8)
	s_branch .Lti_w3j
.Lti_w3f:
	s_waitcnt vmcnt(20)
.Lti_w3j:
	ds_write_b128 v197, v[54:57]
	ds_write_b128 v196, v[66:69]
	ds_write_b128 v195, v[86:89]
	ds_write_b128 v194, v[102:105]
	s_branch .LBB0_1962

	.amdhsa_kernel _Z9trunk_fwd5KArgs
		.amdhsa_group_segment_fixed_size 0
		.amdhsa_private_segment_fixed_size 0
		.amdhsa_kernarg_size 496
		.amdhsa_user_sgpr_count 2
		.amdhsa_user_sgpr_dispatch_ptr 0
		.amdhsa_user_sgpr_queue_ptr 0
		.amdhsa_user_sgpr_kernarg_segment_ptr 1
		.amdhsa_user_sgpr_dispatch_id 0
		.amdhsa_user_sgpr_kernarg_preload_length 0
		.amdhsa_user_sgpr_kernarg_preload_offset 0
		.amdhsa_user_sgpr_private_segment_size 0
		.amdhsa_uses_dynamic_stack 0
		.amdhsa_enable_private_segment 0
		.amdhsa_system_sgpr_workgroup_id_x 1
		.amdhsa_system_sgpr_workgroup_id_y 0
		.amdhsa_system_sgpr_workgroup_id_z 0
		.amdhsa_system_sgpr_workgroup_info 0
		.amdhsa_system_vgpr_workitem_id 0
		.amdhsa_next_free_vgpr 256
		.amdhsa_next_free_sgpr 102
		.amdhsa_accum_offset 256
		.amdhsa_reserve_vcc 1
		.amdhsa_float_round_mode_32 0
		.amdhsa_float_round_mode_16_64 0
		.amdhsa_float_denorm_mode_32 3
		.amdhsa_float_denorm_mode_16_64 3
		.amdhsa_dx10_clamp 1
		.amdhsa_ieee_mode 1
		.amdhsa_fp16_overflow 0
		.amdhsa_tg_split 0
		.amdhsa_exception_fp_ieee_invalid_op 0
		.amdhsa_exception_fp_denorm_src 0
		.amdhsa_exception_fp_ieee_div_zero 0
		.amdhsa_exception_fp_ieee_overflow 0
		.amdhsa_exception_fp_ieee_underflow 0
		.amdhsa_exception_fp_ieee_inexact 0
		.amdhsa_exception_int_div_zero 0
	.end_amdhsa_kernel

amdhsa.kernels:
  - .agpr_count:     0
    .args:
      - .offset:         0
        .size:           240
        .value_kind:     by_value
      - .offset:         240
        .size:           4
        .value_kind:     hidden_block_count_x
      - .offset:         244
        .size:           4
        .value_kind:     hidden_block_count_y
      - .offset:         248
        .size:           4
        .value_kind:     hidden_block_count_z
      - .offset:         252
        .size:           2
        .value_kind:     hidden_group_size_x
      - .offset:         254
        .size:           2
        .value_kind:     hidden_group_size_y
      - .offset:         256
        .size:           2
        .value_kind:     hidden_group_size_z
      - .offset:         258
        .size:           2
        .value_kind:     hidden_remainder_x
      - .offset:         260
        .size:           2
        .value_kind:     hidden_remainder_y
      - .offset:         262
        .size:           2
        .value_kind:     hidden_remainder_z
      - .offset:         280
        .size:           8
        .value_kind:     hidden_global_offset_x
      - .offset:         288
        .size:           8
        .value_kind:     hidden_global_offset_y
      - .offset:         296
        .size:           8
        .value_kind:     hidden_global_offset_z
      - .offset:         304
        .size:           2
        .value_kind:     hidden_grid_dims
      - .offset:         360
        .size:           4
        .value_kind:     hidden_dynamic_lds_size
    .group_segment_fixed_size: 0
    .kernarg_segment_align: 8
    .kernarg_segment_size: 496
    .language:       OpenCL C
    .language_version:
      - 2
      - 0
    .max_flat_workgroup_size: 512
    .name:           _Z9trunk_fwd5KArgs
    .private_segment_fixed_size: 0
    .sgpr_count:     108
    .sgpr_spill_count: 413
    .symbol:         _Z9trunk_fwd5KArgs.kd
    .uniform_work_group_size: 1
    .uses_dynamic_stack: false
    .vgpr_count:     256
    .vgpr_spill_count: 0
    .wavefront_size: 64
